# ret_out: prefetch issue deferred behind the first Q fragment reads; conv_p: fm_load loads batched
# speedup vs baseline: 1.0233x; 1.0029x over previous
; #define FFT_HD __device__ __attribute__((always_inline))
; FFT_HD inline unsigned fm_tidx(int w, int lane, int nt, int q) { return (unsigned)(16 * nt + (lane & 15) + 64 * (8 * w + 2 * (lane >> 4) + q)); }
; template <class BP> FFT_HD inline void fm_load(BP dst, int tid, const float* a, const float* b, bool full) {
; #pragma unroll
;     for (int i = 0; i < 4; ++i) { const int t = tid + 512 * i;
;         *(FFT_LDSU*)(dst + (t & 63) * FM_PITCH + (t >> 6) * 4) = fm_pack(a[t], b[t]);
;         const int t2 = t + 2048;
;         *(FFT_LDSU*)(dst + (t2 & 63) * FM_PITCH + (t2 >> 6) * 4) = full ? fm_pack(a[t2], b[t2]) : 0u; }
; }
; __device__ __forceinline__ void hyena_conv_p(const float* HYT, float* ZOUT, const float* FILT, const unsigned char* fmtab, LAS unsigned char* lds, int vb, int nb, int tid_in) {
;     ...
;             __syncthreads();
;             fm_load(lds + cur * FM_BUF, tid, va, va + 2048, false);
;             float ga[4][2], gb[4][2];
;             if (w < 4) {
; #pragma unroll
;                 for (int nt = 0; nt < 4; ++nt)
; #pragma unroll
;                     for (int q = 0; q < 2; ++q) { const unsigned t = fm_tidx(w, lane, nt, q); ga[nt][q] = x1a[t]; gb[nt][q] = x1a[2048u + t]; } }
.LBB0_692:
	v_lshl_add_u64 v[34:35], v[118:119], 0, s[56:57]
	s_mov_b32 s6, 0x66200000
	v_add_co_u32_e32 v36, vcc, s6, v34
	s_mov_b32 s6, 0x66201000
	s_nop 0
	v_addc_co_u32_e32 v37, vcc, 0, v35, vcc
	v_add_co_u32_e32 v38, vcc, s6, v34
	s_mov_b32 s6, 0x66202000
	s_nop 0
	v_addc_co_u32_e32 v39, vcc, 0, v35, vcc
	v_add_co_u32_e32 v40, vcc, s6, v34
	s_nop 1
	v_addc_co_u32_e32 v41, vcc, 0, v35, vcc
	s_barrier
	global_load_dword v42, v[38:39], off offset:-4096
	global_load_dword v43, v[40:41], off
	v_add_co_u32_e32 v34, vcc, 0x66203000, v34
	global_load_dword v36, v[36:37], off offset:2048
	s_nop 0
	global_load_dword v37, v[40:41], off offset:2048
	v_addc_co_u32_e32 v35, vcc, 0, v35, vcc
	s_andn2_b64 vcc, exec, s[50:51]
	global_load_dword v212, v[38:39], off
	global_load_dword v213, v[34:35], off
	global_load_dword v214, v[38:39], off offset:2048
	global_load_dword v215, v[34:35], off offset:2048
	s_waitcnt vmcnt(6)
	v_cvt_pk_f16_f32 v42, v42, v43
	ds_write_b32 v236, v42
	ds_write_b32 v237, v183
	s_waitcnt vmcnt(4)
	v_cvt_pk_f16_f32 v36, v36, v37
	ds_write_b32 v238, v36
	ds_write_b32 v239, v183
	s_waitcnt vmcnt(2)
	v_cvt_pk_f16_f32 v36, v212, v213
	ds_write_b32 v240, v36
	ds_write_b32 v241, v183
	s_waitcnt vmcnt(0)
	v_cvt_pk_f16_f32 v34, v214, v215
	ds_write_b32 v242, v34
	ds_write_b32 v243, v183
	v_cndmask_b32_e64 v34, 0, 1, s[50:51]
	v_cmp_ne_u32_e64 s[6:7], 1, v34
	s_cbranch_vccnz .LBB0_694
	v_lshl_add_u64 v[34:35], v[126:127], 0, s[56:57]
	v_add_co_u32_e32 v34, vcc, 0x66200000, v34
	v_lshl_add_u64 v[36:37], v[128:129], 0, s[56:57]
	s_nop 0
	v_addc_co_u32_e32 v35, vcc, 0, v35, vcc
	global_load_dword v185, v[34:35], off
	global_load_dword v189, v[36:37], off
	global_load_dword v186, v[34:35], off offset:256
	v_lshl_add_u64 v[36:37], v[130:131], 0, s[56:57]
	global_load_dword v192, v[36:37], off
	global_load_dword v190, v[34:35], off offset:64
	v_lshl_add_u64 v[36:37], v[132:133], 0, s[56:57]
	global_load_dword v225, v[36:37], off
	v_lshl_add_u64 v[36:37], v[124:125], 0, s[56:57]
	global_load_dword v226, v[36:37], off
	v_lshl_add_u64 v[36:37], v[134:135], 0, s[56:57]
	global_load_dword v228, v[36:37], off
	global_load_dword v227, v[34:35], off offset:128
	v_lshl_add_u64 v[36:37], v[136:137], 0, s[56:57]
	global_load_dword v229, v[36:37], off
	v_lshl_add_u64 v[36:37], v[122:123], 0, s[56:57]
	global_load_dword v230, v[36:37], off
	v_lshl_add_u64 v[36:37], v[138:139], 0, s[56:57]
	global_load_dword v231, v[36:37], off
	global_load_dword v232, v[34:35], off offset:192
	v_lshl_add_u64 v[34:35], v[140:141], 0, s[56:57]
	global_load_dword v233, v[34:35], off
	v_lshl_add_u64 v[34:35], v[120:121], 0, s[56:57]
	global_load_dword v234, v[34:35], off
	v_lshl_add_u64 v[34:35], v[142:143], 0, s[56:57]
	global_load_dword v235, v[34:35], off

; __device__ __forceinline__ float ret_log_gamma(const float* dexp, int dir, int h) { return log1pf(-exp2f(-dexp[dir * 8 + h])); }
; __device__ __forceinline__ void ret_fix(bf16* ST, const bf16* FS, const float* dexp, int vb, int nb, int tid) {
;     for (int it = vb; it < 64 * 8 * 2; it += nb) {
;         const int dir = it & 1, h = (it >> 1) & 7, cl = it >> 4, sg = cl >> 4, nl = cl & 15;
;         const int ncar = dir == 0 ? sg : 3 - sg;
;         if (ncar == 0) continue;
;         const bool loc = dir == 0 ? nl > 0 : nl < 15;
;         const float lgd = ret_log_gamma(dexp, dir, h), c0 = __expf(lgd * 128.0f * (float)(dir == 0 ? nl : 15 - nl)), cs = __expf(lgd * 2048.0f);
;         float cf[3]; cf[0] = c0; cf[1] = c0 * cs; cf[2] = c0 * cs * cs;
;         bf16* dst = ST + ((size_t)((128 + cl) * 8 + h) * 2 + dir) * 65536;
; __device__ __forceinline__ void hyena_conv_p(const float* HYT, float* ZOUT, const float* FILT, const unsigned char* fmtab, LAS unsigned char* lds, int vb, int nb, int tid_in) {
;     ...
;     __syncthreads();
.LBB0_703:
	v_mov_b32_e32 v212, 1
	v_mov_b32_e32 v213, 0x3ecc95a3
	v_mov_b32_e32 v214, 0x358637bd
	v_mov_b32_e32 v215, 0x260
	s_and_b64 vcc, exec, s[4:5]
	s_mov_b32 s50, 0x1e3ce508
	s_barrier
	s_cbranch_vccnz .LBB0_767
	s_load_dwordx2 s[4:5], s[10:11], 0x80
	s_add_u32 s3, s8, 0x78200000
	s_addc_u32 s26, s9, 0
	v_readlane_b32 s6, v251, 14
	s_add_u32 s27, s8, 0x96200000
	v_readlane_b32 s7, v251, 15
	s_addc_u32 s28, s9, 0
	s_lshl_b64 s[6:7], s[6:7], 2
	s_waitcnt lgkmcnt(0)
	s_add_u32 s14, s4, s6
	v_mov_b32_e32 v2, 0
	s_addc_u32 s15, s5, s7
	v_mov_b32_e32 v3, v2
	v_mov_b32_e32 v4, v2
	v_mov_b32_e32 v5, v2
	v_mov_b32_e32 v6, v2
	v_mov_b32_e32 v7, v2
	v_mov_b32_e32 v8, v2
	v_mov_b32_e32 v9, v2
	v_mov_b32_e32 v10, v2
	v_mov_b32_e32 v11, v2
	v_mov_b32_e32 v12, v2
	v_mov_b32_e32 v13, v2
	s_branch .LBB0_707

; #define LAS __attribute__((address_space(3)))
; __device__ __forceinline__ unsigned pk2(float lo, float hi) { const f32x2 v = {lo, hi}; return __builtin_bit_cast(unsigned, __builtin_convertvector(v, bf16x2_t)); }
; __device__ __forceinline__ void ret_out(const bf16* proj, const bf16* ST, bf16* mixed, const float* dexp, LAS unsigned char* lds, int vb, int nb, int tid_in0, int wave) {
;     ...
;             __syncthreads();
;             if (have) {
; #pragma unroll
;                 for (int i = 0; i < 16; ++i) { const int id = tid + 512 * i; *(LAS v4u*)(Sx + (id >> 5) * 528 + (id & 31) * 16) = pf[i]; } }
;             __syncthreads();
;             if (dir == 0) { if (have_b) { const bf16* src = ST + ((size_t)(gc * 8 + h) * 2 + 1) * 65536;
; #pragma unroll
;                     for (int i = 0; i < 16; ++i) { const int id = tid + 512 * i; pf[i] = *(const v4u*)(src + (id >> 5) * 256 + (id & 31) * 8); } } }
;             else { const int un = unit + nb;
;                 if (un < 1536) { const int gc2 = un >> 3, h2 = un & 7, rowb2 = gc2 * 128;
; #pragma unroll
;                     for (int i = 0; i < 8; ++i) { const int id = tid + 512 * i, j = id >> 5, ch = id & 31;
;                         pf[i] = *(const v4u*)(proj + (size_t)(rowb2 + j) * NIN + C_RK + h2 * 256 + ch * 8); pf[8 + i] = *(const v4u*)(proj + (size_t)(rowb2 + j) * NIN + C_RV + h2 * 256 + ch * 8); } } }
;             if (have) {
;                 const float xi = dir == 0 ? __expf(lgf * (float)(iq + 1)) : __expf(lgb * (float)(128 - iq));
; #pragma unroll
;                 for (int kh = 0; kh < 2; ++kh) {
;                     bf16x8 qs[4];
; #pragma unroll
;                     for (int k4 = 0; k4 < 4; ++k4) { const int ks = 4 * kh + k4; const v4u q = *(const v4u*)(proj + (size_t)qrow * NIN + C_RQ + h * 256 + ks * 32 + g * 8); v4u r;
;                         r.x = pk2(bflo(q.x) * xi, bfhi(q.x) * xi); r.y = pk2(bflo(q.y) * xi, bfhi(q.y) * xi); r.z = pk2(bflo(q.z) * xi, bfhi(q.z) * xi); r.w = pk2(bflo(q.w) * xi, bfhi(q.w) * xi);
;                         qs[k4] = __builtin_bit_cast(bf16x8, r); }
.LBB0_840:
	s_and_b64 s[28:29], s[42:43], exec
	s_cselect_b32 s15, 15, 63
	s_cmp_lt_i32 s26, s15
	s_cselect_b64 s[42:43], -1, 0
	s_cmp_ge_i32 s26, s15
	s_waitcnt lgkmcnt(0)
	s_barrier
	s_cbranch_scc1 .LBB0_842
	s_and_b64 vcc, exec, s[50:51]
	s_cbranch_vccnz .LBB0_842
	s_add_u32 s6, s56, s6
	s_addc_u32 s7, s57, s7
	v_and_b32_e32 v60, 0xffffff00, v233
	v_lshl_add_u64 v[2:3], v[182:183], 1, s[6:7]
	s_mov_b64 s[6:7], 0x20000
	v_add_u32_e32 v4, 0x1000, v60
	v_add_u32_e32 v10, 0x2000, v60
	v_add_u32_e32 v12, 0x3000, v60
	v_add_u32_e32 v18, 0x4000, v60
	v_add_u32_e32 v20, 0x5000, v60
	v_lshl_add_u64 v[58:59], v[2:3], 0, s[6:7]
	v_ashrrev_i32_e32 v61, 31, v60
	v_ashrrev_i32_e32 v5, 31, v4
	v_ashrrev_i32_e32 v11, 31, v10
	v_ashrrev_i32_e32 v13, 31, v12
	v_ashrrev_i32_e32 v19, 31, v18
	v_ashrrev_i32_e32 v21, 31, v20
	v_lshl_add_u64 v[2:3], v[60:61], 1, v[58:59]
	v_lshl_add_u64 v[6:7], v[4:5], 1, v[58:59]
	v_lshl_add_u64 v[10:11], v[10:11], 1, v[58:59]
	v_lshl_add_u64 v[14:15], v[12:13], 1, v[58:59]
	v_lshl_add_u64 v[18:19], v[18:19], 1, v[58:59]
	v_lshl_add_u64 v[20:21], v[20:21], 1, v[58:59]
	global_load_dwordx4 v[2:5], v[2:3], off
	s_nop 0
	global_load_dwordx4 v[6:9], v[6:7], off
	s_nop 0
	global_load_dwordx4 v[10:13], v[10:11], off
	s_nop 0
	global_load_dwordx4 v[14:17], v[14:15], off
	s_nop 0
	global_load_dwordx4 v[26:29], v[18:19], off
	global_load_dwordx4 v[30:33], v[20:21], off
	v_add_u32_e32 v18, 0x6000, v60
	v_add_u32_e32 v20, 0x7000, v60
	v_ashrrev_i32_e32 v19, 31, v18
	v_ashrrev_i32_e32 v21, 31, v20
	v_lshl_add_u64 v[18:19], v[18:19], 1, v[58:59]
	v_lshl_add_u64 v[20:21], v[20:21], 1, v[58:59]
	global_load_dwordx4 v[42:45], v[18:19], off
	global_load_dwordx4 v[46:49], v[20:21], off
	v_add_u32_e32 v18, 0x8000, v60
	v_add_u32_e32 v20, 0x9000, v60
	v_add_u32_e32 v34, 0xa000, v60
	v_add_u32_e32 v36, 0xb000, v60
	v_add_u32_e32 v50, 0xc000, v60
	v_add_u32_e32 v52, 0xd000, v60
	v_add_u32_e32 v62, 0xe000, v60
	v_add_u32_e32 v60, 0xf000, v60
	v_ashrrev_i32_e32 v19, 31, v18
	v_ashrrev_i32_e32 v21, 31, v20
	v_ashrrev_i32_e32 v35, 31, v34
	v_ashrrev_i32_e32 v37, 31, v36
	v_ashrrev_i32_e32 v51, 31, v50
	v_ashrrev_i32_e32 v53, 31, v52
	v_ashrrev_i32_e32 v63, 31, v62
	v_ashrrev_i32_e32 v61, 31, v60
	v_lshl_add_u64 v[18:19], v[18:19], 1, v[58:59]
	v_lshl_add_u64 v[22:23], v[20:21], 1, v[58:59]
	v_lshl_add_u64 v[34:35], v[34:35], 1, v[58:59]
	v_lshl_add_u64 v[38:39], v[36:37], 1, v[58:59]
	v_lshl_add_u64 v[50:51], v[50:51], 1, v[58:59]
	v_lshl_add_u64 v[54:55], v[52:53], 1, v[58:59]
	v_lshl_add_u64 v[62:63], v[62:63], 1, v[58:59]
	v_lshl_add_u64 v[64:65], v[60:61], 1, v[58:59]
	global_load_dwordx4 v[18:21], v[18:19], off
	s_nop 0
	global_load_dwordx4 v[22:25], v[22:23], off
	s_nop 0
	global_load_dwordx4 v[34:37], v[34:35], off
	s_nop 0
	global_load_dwordx4 v[38:41], v[38:39], off
	s_nop 0
	global_load_dwordx4 v[50:53], v[50:51], off
	s_nop 0
	global_load_dwordx4 v[54:57], v[54:55], off
	s_nop 0
	global_load_dwordx4 v[58:61], v[62:63], off
	s_nop 0
	global_load_dwordx4 v[62:65], v[64:65], off
.LBB0_842:
	v_mul_u32_u24_e32 v130, 0x210, v231
	v_add_u32_e32 v155, 0x10800, v130
	v_add_u32_e32 v154, 0x12900, v130
	v_add_u32_e32 v153, 0x14a00, v130
	v_add_u32_e32 v152, 0x16b00, v130
	v_add_u32_e32 v151, 0x18c00, v130
	v_add_u32_e32 v150, 0x1ad00, v130
	v_add_u32_e32 v149, 0x1ce00, v130
	v_add_u32_e32 v147, 0x1ef00, v130
	s_and_b64 vcc, exec, s[4:5]
	v_add_u32_e32 v156, v234, v130
	v_add_u32_e32 v164, v234, v155
	v_add_u32_e32 v163, v234, v154
	v_add_u32_e32 v162, v234, v153
	v_add_u32_e32 v161, v234, v152
	v_add_u32_e32 v160, v234, v151
	v_add_u32_e32 v159, v234, v150
	v_add_u32_e32 v158, v234, v149
	v_add_u32_e32 v157, v234, v147
	v_add_u32_e32 v148, 0x100, v234
	s_cbranch_vccnz .LBB0_844
	v_add_u32_e32 v130, 1, v189
	v_cvt_f32_i32_e32 v130, v130
	v_mul_f32_e32 v130, v235, v130
	v_mul_f32_e32 v130, 0x3fb8aa3b, v130
	v_exp_f32_e32 v146, v130
	global_load_dwordx4 v[130:133], v[202:203], off
	s_waitcnt vmcnt(0)
	v_lshlrev_b32_e32 v134, 16, v130
	v_and_b32_e32 v135, 0xffff0000, v130
	v_pk_mul_f32 v[134:135], v[146:147], v[134:135] op_sel_hi:[0,1]
	v_cvt_pk_bf16_f32 v130, v134, v135
	v_lshlrev_b32_e32 v134, 16, v131
	v_and_b32_e32 v135, 0xffff0000, v131
	v_pk_mul_f32 v[134:135], v[146:147], v[134:135] op_sel_hi:[0,1]
	v_cvt_pk_bf16_f32 v131, v134, v135
	v_lshlrev_b32_e32 v134, 16, v132
	v_and_b32_e32 v135, 0xffff0000, v132
	v_pk_mul_f32 v[134:135], v[146:147], v[134:135] op_sel_hi:[0,1]
	v_cvt_pk_bf16_f32 v132, v134, v135
	v_lshlrev_b32_e32 v134, 16, v133
	v_and_b32_e32 v135, 0xffff0000, v133
	v_pk_mul_f32 v[134:135], v[146:147], v[134:135] op_sel_hi:[0,1]
	v_cvt_pk_bf16_f32 v133, v134, v135
	global_load_dwordx4 v[134:137], v[202:203], off offset:64
	s_waitcnt vmcnt(0)
	v_lshlrev_b32_e32 v138, 16, v134
	v_and_b32_e32 v139, 0xffff0000, v134
	v_pk_mul_f32 v[138:139], v[146:147], v[138:139] op_sel_hi:[0,1]
	v_cvt_pk_bf16_f32 v134, v138, v139
	v_lshlrev_b32_e32 v138, 16, v135
	v_and_b32_e32 v139, 0xffff0000, v135
	v_pk_mul_f32 v[138:139], v[146:147], v[138:139] op_sel_hi:[0,1]
	v_cvt_pk_bf16_f32 v135, v138, v139
	v_lshlrev_b32_e32 v138, 16, v136
	v_and_b32_e32 v139, 0xffff0000, v136
	v_pk_mul_f32 v[138:139], v[146:147], v[138:139] op_sel_hi:[0,1]
	v_cvt_pk_bf16_f32 v136, v138, v139
	v_lshlrev_b32_e32 v138, 16, v137
	v_and_b32_e32 v139, 0xffff0000, v137
	v_pk_mul_f32 v[138:139], v[146:147], v[138:139] op_sel_hi:[0,1]
	v_cvt_pk_bf16_f32 v137, v138, v139
	global_load_dwordx4 v[138:141], v[202:203], off offset:128
	s_waitcnt vmcnt(0)
	v_lshlrev_b32_e32 v142, 16, v138
	v_and_b32_e32 v143, 0xffff0000, v138
	v_pk_mul_f32 v[142:143], v[146:147], v[142:143] op_sel_hi:[0,1]
	v_cvt_pk_bf16_f32 v138, v142, v143
	v_lshlrev_b32_e32 v142, 16, v139
	v_and_b32_e32 v143, 0xffff0000, v139
	v_pk_mul_f32 v[142:143], v[146:147], v[142:143] op_sel_hi:[0,1]
	v_cvt_pk_bf16_f32 v139, v142, v143
	v_lshlrev_b32_e32 v142, 16, v140
	v_and_b32_e32 v143, 0xffff0000, v140
	v_pk_mul_f32 v[142:143], v[146:147], v[142:143] op_sel_hi:[0,1]
	v_cvt_pk_bf16_f32 v140, v142, v143
	v_lshlrev_b32_e32 v142, 16, v141
	v_and_b32_e32 v143, 0xffff0000, v141
	v_pk_mul_f32 v[142:143], v[146:147], v[142:143] op_sel_hi:[0,1]
	v_cvt_pk_bf16_f32 v141, v142, v143
	global_load_dwordx4 v[142:145], v[202:203], off offset:192
	s_waitcnt vmcnt(0)
	v_lshlrev_b32_e32 v174, 16, v142
	v_and_b32_e32 v175, 0xffff0000, v142
	v_pk_mul_f32 v[174:175], v[146:147], v[174:175] op_sel_hi:[0,1]
	v_cvt_pk_bf16_f32 v142, v174, v175
	v_lshlrev_b32_e32 v174, 16, v143
	v_and_b32_e32 v175, 0xffff0000, v143
	v_pk_mul_f32 v[174:175], v[146:147], v[174:175] op_sel_hi:[0,1]
	v_cvt_pk_bf16_f32 v143, v174, v175
	v_lshlrev_b32_e32 v174, 16, v144
	v_and_b32_e32 v175, 0xffff0000, v144
	v_pk_mul_f32 v[174:175], v[146:147], v[174:175] op_sel_hi:[0,1]
	v_cvt_pk_bf16_f32 v144, v174, v175
	v_lshlrev_b32_e32 v174, 16, v145
	v_and_b32_e32 v175, 0xffff0000, v145
	v_pk_mul_f32 v[174:175], v[146:147], v[174:175] op_sel_hi:[0,1]
	v_cvt_pk_bf16_f32 v145, v174, v175
	s_cmp_ge_i32 s26, s15
	s_cbranch_scc1 .Lro_nopf_d0
; #define LAS __attribute__((address_space(3)))
; __device__ __forceinline__ f32x4 mfma16(bf16x8 a, bf16x8 b, f32x4 c) { return __builtin_amdgcn_mfma_f32_16x16x32_bf16(a, b, c, 0, 0, 0); }
; __device__ __forceinline__ void ret_out(const bf16* proj, const bf16* ST, bf16* mixed, const float* dexp, LAS unsigned char* lds, int vb, int nb, int tid_in0, int wave) {
;     ...
;             if (dir == 0) { if (have_b) { const bf16* src = ST + ((size_t)(gc * 8 + h) * 2 + 1) * 65536;
; #pragma unroll
;                     for (int i = 0; i < 16; ++i) { const int id = tid + 512 * i; pf[i] = *(const v4u*)(src + (id >> 5) * 256 + (id & 31) * 8); } } }
;     ...
; #pragma unroll
;                     for (int v = 0; v < 16; ++v) {
;                         const LAS unsigned char* sp = Sx + (v * 16 + qi) * 528 + g * 16 + kh * 256;
; #pragma unroll
;                         for (int k4 = 0; k4 < 4; ++k4) o[v] = mfma16(*(const LAS bf16x8*)(sp + k4 * 64), qs[k4], o[v]);
;                         if ((v & 1) == 1) asm volatile("" ::: "memory");
	s_add_u32 s6, s56, s6
	s_addc_u32 s7, s57, s7
	v_and_b32_e32 v60, 0xffffff00, v233
	v_lshl_add_u64 v[2:3], v[182:183], 1, s[6:7]
	s_mov_b64 s[6:7], 0x20000
	v_add_u32_e32 v4, 0x1000, v60
	v_add_u32_e32 v10, 0x2000, v60
	v_add_u32_e32 v12, 0x3000, v60
	v_add_u32_e32 v18, 0x4000, v60
	v_add_u32_e32 v20, 0x5000, v60
	v_lshl_add_u64 v[58:59], v[2:3], 0, s[6:7]
	v_ashrrev_i32_e32 v61, 31, v60
	v_ashrrev_i32_e32 v5, 31, v4
	v_ashrrev_i32_e32 v11, 31, v10
	v_ashrrev_i32_e32 v13, 31, v12
	v_ashrrev_i32_e32 v19, 31, v18
	v_ashrrev_i32_e32 v21, 31, v20
	v_lshl_add_u64 v[2:3], v[60:61], 1, v[58:59]
	v_lshl_add_u64 v[6:7], v[4:5], 1, v[58:59]
	v_lshl_add_u64 v[10:11], v[10:11], 1, v[58:59]
	v_lshl_add_u64 v[14:15], v[12:13], 1, v[58:59]
	v_lshl_add_u64 v[18:19], v[18:19], 1, v[58:59]
	v_lshl_add_u64 v[20:21], v[20:21], 1, v[58:59]
	global_load_dwordx4 v[2:5], v[2:3], off
	s_nop 0
	global_load_dwordx4 v[6:9], v[6:7], off
	s_nop 0
	global_load_dwordx4 v[10:13], v[10:11], off
	s_nop 0
	global_load_dwordx4 v[14:17], v[14:15], off
	s_nop 0
	global_load_dwordx4 v[26:29], v[18:19], off
	global_load_dwordx4 v[30:33], v[20:21], off
	v_add_u32_e32 v18, 0x6000, v60
	v_add_u32_e32 v20, 0x7000, v60
	v_ashrrev_i32_e32 v19, 31, v18
	v_ashrrev_i32_e32 v21, 31, v20
	v_lshl_add_u64 v[18:19], v[18:19], 1, v[58:59]
	v_lshl_add_u64 v[20:21], v[20:21], 1, v[58:59]
	global_load_dwordx4 v[42:45], v[18:19], off
	global_load_dwordx4 v[46:49], v[20:21], off
	v_add_u32_e32 v18, 0x8000, v60
	v_add_u32_e32 v20, 0x9000, v60
	v_add_u32_e32 v34, 0xa000, v60
	v_add_u32_e32 v36, 0xb000, v60
	v_add_u32_e32 v50, 0xc000, v60
	v_add_u32_e32 v52, 0xd000, v60
	v_add_u32_e32 v62, 0xe000, v60
	v_add_u32_e32 v60, 0xf000, v60
	v_ashrrev_i32_e32 v19, 31, v18
	v_ashrrev_i32_e32 v21, 31, v20
	v_ashrrev_i32_e32 v35, 31, v34
	v_ashrrev_i32_e32 v37, 31, v36
	v_ashrrev_i32_e32 v51, 31, v50
	v_ashrrev_i32_e32 v53, 31, v52
	v_ashrrev_i32_e32 v63, 31, v62
	v_ashrrev_i32_e32 v61, 31, v60
	v_lshl_add_u64 v[18:19], v[18:19], 1, v[58:59]
	v_lshl_add_u64 v[22:23], v[20:21], 1, v[58:59]
	v_lshl_add_u64 v[34:35], v[34:35], 1, v[58:59]
	v_lshl_add_u64 v[38:39], v[36:37], 1, v[58:59]
	v_lshl_add_u64 v[50:51], v[50:51], 1, v[58:59]
	v_lshl_add_u64 v[54:55], v[52:53], 1, v[58:59]
	v_lshl_add_u64 v[62:63], v[62:63], 1, v[58:59]
	v_lshl_add_u64 v[64:65], v[60:61], 1, v[58:59]
	global_load_dwordx4 v[18:21], v[18:19], off
	s_nop 0
	global_load_dwordx4 v[22:25], v[22:23], off
	s_nop 0
	global_load_dwordx4 v[34:37], v[34:35], off
	s_nop 0
	global_load_dwordx4 v[38:41], v[38:39], off
	s_nop 0
	global_load_dwordx4 v[50:53], v[50:51], off
	s_nop 0
	global_load_dwordx4 v[54:57], v[54:55], off
	s_nop 0
	global_load_dwordx4 v[58:61], v[62:63], off
	s_nop 0
	global_load_dwordx4 v[62:65], v[64:65], off
.Lro_nopf_d0:
	ds_read_b128 v[174:177], v156
	s_waitcnt lgkmcnt(0)
	v_mfma_f32_16x16x32_bf16 v[122:125], v[174:177], v[130:133], v[122:125]
	ds_read_b128 v[174:177], v156 offset:64
	s_waitcnt lgkmcnt(0)
	v_mfma_f32_16x16x32_bf16 v[122:125], v[174:177], v[134:137], v[122:125]
	ds_read_b128 v[174:177], v156 offset:128
	s_waitcnt lgkmcnt(0)
	v_mfma_f32_16x16x32_bf16 v[122:125], v[174:177], v[138:141], v[122:125]
	ds_read_b128 v[174:177], v156 offset:192
	s_waitcnt lgkmcnt(0)
	v_mfma_f32_16x16x32_bf16 v[122:125], v[174:177], v[142:145], v[122:125]
	ds_read_b128 v[174:177], v156 offset:8640
	ds_read_b128 v[178:181], v156 offset:8576
	ds_read_b128 v[232:235], v156 offset:8512
	ds_read_b128 v[236:239], v156 offset:8448
	s_waitcnt lgkmcnt(0)
	v_mfma_f32_16x16x32_bf16 v[126:129], v[236:239], v[130:133], v[126:129]
	v_mfma_f32_16x16x32_bf16 v[126:129], v[232:235], v[134:137], v[126:129]
	v_mfma_f32_16x16x32_bf16 v[126:129], v[178:181], v[138:141], v[126:129]
	v_mfma_f32_16x16x32_bf16 v[126:129], v[174:177], v[142:145], v[126:129]
	ds_read_b128 v[174:177], v156 offset:16896
	s_waitcnt lgkmcnt(0)
	v_mfma_f32_16x16x32_bf16 v[118:121], v[174:177], v[130:133], v[118:121]
	ds_read_b128 v[174:177], v156 offset:16960
	s_waitcnt lgkmcnt(0)
	v_mfma_f32_16x16x32_bf16 v[118:121], v[174:177], v[134:137], v[118:121]
	ds_read_b128 v[174:177], v156 offset:17024
	s_waitcnt lgkmcnt(0)
	v_mfma_f32_16x16x32_bf16 v[118:121], v[174:177], v[138:141], v[118:121]
	ds_read_b128 v[174:177], v156 offset:17088
	s_waitcnt lgkmcnt(0)
	v_mfma_f32_16x16x32_bf16 v[118:121], v[174:177], v[142:145], v[118:121]
	ds_read_b128 v[174:177], v156 offset:25536
	ds_read_b128 v[178:181], v156 offset:25472
	ds_read_b128 v[232:235], v156 offset:25408
	ds_read_b128 v[236:239], v156 offset:25344
	s_waitcnt lgkmcnt(0)
	v_mfma_f32_16x16x32_bf16 v[114:117], v[236:239], v[130:133], v[114:117]
	v_mfma_f32_16x16x32_bf16 v[114:117], v[232:235], v[134:137], v[114:117]
	v_mfma_f32_16x16x32_bf16 v[114:117], v[178:181], v[138:141], v[114:117]
	v_mfma_f32_16x16x32_bf16 v[114:117], v[174:177], v[142:145], v[114:117]
	ds_read_b128 v[174:177], v156 offset:33792
	s_waitcnt lgkmcnt(0)
	v_mfma_f32_16x16x32_bf16 v[110:113], v[174:177], v[130:133], v[110:113]
	ds_read_b128 v[174:177], v156 offset:33856
	s_waitcnt lgkmcnt(0)
	v_mfma_f32_16x16x32_bf16 v[110:113], v[174:177], v[134:137], v[110:113]
	ds_read_b128 v[174:177], v156 offset:33920
	s_waitcnt lgkmcnt(0)
	v_mfma_f32_16x16x32_bf16 v[110:113], v[174:177], v[138:141], v[110:113]
	ds_read_b128 v[174:177], v156 offset:33984
	s_waitcnt lgkmcnt(0)
	v_mfma_f32_16x16x32_bf16 v[110:113], v[174:177], v[142:145], v[110:113]
	ds_read_b128 v[174:177], v156 offset:42432
	ds_read_b128 v[178:181], v156 offset:42368
	ds_read_b128 v[232:235], v156 offset:42304
	ds_read_b128 v[236:239], v156 offset:42240
	s_waitcnt lgkmcnt(0)
; #define LAS __attribute__((address_space(3)))
; __device__ __forceinline__ f32x4 mfma16(bf16x8 a, bf16x8 b, f32x4 c) { return __builtin_amdgcn_mfma_f32_16x16x32_bf16(a, b, c, 0, 0, 0); }
; __device__ __forceinline__ void ret_out(const bf16* proj, const bf16* ST, bf16* mixed, const float* dexp, LAS unsigned char* lds, int vb, int nb, int tid_in0, int wave) {
;     ...
;                     for (int k4 = 0; k4 < 4; ++k4) { const int ks = 4 * kh + k4; const v4u q = *(const v4u*)(proj + (size_t)qrow * NIN + C_RQ + h * 256 + ks * 32 + g * 8); v4u r;
;     ...
; #pragma unroll
;                     for (int v = 0; v < 16; ++v) {
;                         const LAS unsigned char* sp = Sx + (v * 16 + qi) * 528 + g * 16 + kh * 256;
; #pragma unroll
;                         for (int k4 = 0; k4 < 4; ++k4) o[v] = mfma16(*(const LAS bf16x8*)(sp + k4 * 64), qs[k4], o[v]);
;                         if ((v & 1) == 1) asm volatile("" ::: "memory");
	v_mfma_f32_16x16x32_bf16 v[106:109], v[236:239], v[130:133], v[106:109]
	v_mfma_f32_16x16x32_bf16 v[106:109], v[232:235], v[134:137], v[106:109]
	v_mfma_f32_16x16x32_bf16 v[106:109], v[178:181], v[138:141], v[106:109]
	v_mfma_f32_16x16x32_bf16 v[106:109], v[174:177], v[142:145], v[106:109]
	ds_read_b128 v[174:177], v156 offset:50688
	s_waitcnt lgkmcnt(0)
	v_mfma_f32_16x16x32_bf16 v[102:105], v[174:177], v[130:133], v[102:105]
	ds_read_b128 v[174:177], v156 offset:50752
	s_waitcnt lgkmcnt(0)
	v_mfma_f32_16x16x32_bf16 v[102:105], v[174:177], v[134:137], v[102:105]
	ds_read_b128 v[174:177], v156 offset:50816
	s_waitcnt lgkmcnt(0)
	v_mfma_f32_16x16x32_bf16 v[102:105], v[174:177], v[138:141], v[102:105]
	ds_read_b128 v[174:177], v156 offset:50880
	s_waitcnt lgkmcnt(0)
	v_mfma_f32_16x16x32_bf16 v[102:105], v[174:177], v[142:145], v[102:105]
	ds_read_b128 v[174:177], v156 offset:59328
	ds_read_b128 v[178:181], v156 offset:59264
	ds_read_b128 v[232:235], v156 offset:59200
	ds_read_b128 v[236:239], v156 offset:59136
	s_waitcnt lgkmcnt(0)
	v_mfma_f32_16x16x32_bf16 v[98:101], v[236:239], v[130:133], v[98:101]
	v_mfma_f32_16x16x32_bf16 v[98:101], v[232:235], v[134:137], v[98:101]
	v_mfma_f32_16x16x32_bf16 v[98:101], v[178:181], v[138:141], v[98:101]
	v_mfma_f32_16x16x32_bf16 v[98:101], v[174:177], v[142:145], v[98:101]
	ds_read_b128 v[174:177], v164
	s_waitcnt lgkmcnt(0)
	v_mfma_f32_16x16x32_bf16 v[94:97], v[174:177], v[130:133], v[94:97]
	ds_read_b128 v[174:177], v164 offset:64
	s_waitcnt lgkmcnt(0)
	v_mfma_f32_16x16x32_bf16 v[94:97], v[174:177], v[134:137], v[94:97]
	ds_read_b128 v[174:177], v164 offset:128
	s_waitcnt lgkmcnt(0)
	v_mfma_f32_16x16x32_bf16 v[94:97], v[174:177], v[138:141], v[94:97]
	ds_read_b128 v[174:177], v164 offset:192
	s_waitcnt lgkmcnt(0)
	v_mfma_f32_16x16x32_bf16 v[94:97], v[174:177], v[142:145], v[94:97]
	ds_read_b128 v[174:177], v163
	s_waitcnt lgkmcnt(0)
	v_mfma_f32_16x16x32_bf16 v[90:93], v[174:177], v[130:133], v[90:93]
	ds_read_b128 v[174:177], v163 offset:64
	s_waitcnt lgkmcnt(0)
	v_mfma_f32_16x16x32_bf16 v[90:93], v[174:177], v[134:137], v[90:93]
	ds_read_b128 v[174:177], v163 offset:128
	s_waitcnt lgkmcnt(0)
	v_mfma_f32_16x16x32_bf16 v[90:93], v[174:177], v[138:141], v[90:93]
	ds_read_b128 v[174:177], v163 offset:192
	s_waitcnt lgkmcnt(0)
	v_mfma_f32_16x16x32_bf16 v[90:93], v[174:177], v[142:145], v[90:93]
	ds_read_b128 v[174:177], v162
	s_waitcnt lgkmcnt(0)
	v_mfma_f32_16x16x32_bf16 v[86:89], v[174:177], v[130:133], v[86:89]
	ds_read_b128 v[174:177], v162 offset:64
	s_waitcnt lgkmcnt(0)
	v_mfma_f32_16x16x32_bf16 v[86:89], v[174:177], v[134:137], v[86:89]
	ds_read_b128 v[174:177], v162 offset:128
	s_waitcnt lgkmcnt(0)
	v_mfma_f32_16x16x32_bf16 v[86:89], v[174:177], v[138:141], v[86:89]
	ds_read_b128 v[174:177], v162 offset:192
	s_waitcnt lgkmcnt(0)
	v_mfma_f32_16x16x32_bf16 v[86:89], v[174:177], v[142:145], v[86:89]
	ds_read_b128 v[174:177], v161
	s_waitcnt lgkmcnt(0)
	v_mfma_f32_16x16x32_bf16 v[82:85], v[174:177], v[130:133], v[82:85]
	ds_read_b128 v[174:177], v161 offset:64
	s_waitcnt lgkmcnt(0)
	v_mfma_f32_16x16x32_bf16 v[82:85], v[174:177], v[134:137], v[82:85]
	ds_read_b128 v[174:177], v161 offset:128
	s_waitcnt lgkmcnt(0)
	v_mfma_f32_16x16x32_bf16 v[82:85], v[174:177], v[138:141], v[82:85]
	ds_read_b128 v[174:177], v161 offset:192
	s_waitcnt lgkmcnt(0)
	v_mfma_f32_16x16x32_bf16 v[82:85], v[174:177], v[142:145], v[82:85]
	ds_read_b128 v[174:177], v160
	s_waitcnt lgkmcnt(0)
	v_mfma_f32_16x16x32_bf16 v[78:81], v[174:177], v[130:133], v[78:81]
	ds_read_b128 v[174:177], v160 offset:64
	s_waitcnt lgkmcnt(0)
	v_mfma_f32_16x16x32_bf16 v[78:81], v[174:177], v[134:137], v[78:81]
	ds_read_b128 v[174:177], v160 offset:128
	s_waitcnt lgkmcnt(0)
	v_mfma_f32_16x16x32_bf16 v[78:81], v[174:177], v[138:141], v[78:81]
	ds_read_b128 v[174:177], v160 offset:192
	s_waitcnt lgkmcnt(0)
	v_mfma_f32_16x16x32_bf16 v[78:81], v[174:177], v[142:145], v[78:81]
	ds_read_b128 v[174:177], v159
	s_waitcnt lgkmcnt(0)
	v_mfma_f32_16x16x32_bf16 v[74:77], v[174:177], v[130:133], v[74:77]
	ds_read_b128 v[174:177], v159 offset:64
	s_waitcnt lgkmcnt(0)
	v_mfma_f32_16x16x32_bf16 v[74:77], v[174:177], v[134:137], v[74:77]
	ds_read_b128 v[174:177], v159 offset:128
	s_waitcnt lgkmcnt(0)
	v_mfma_f32_16x16x32_bf16 v[74:77], v[174:177], v[138:141], v[74:77]
	ds_read_b128 v[174:177], v159 offset:192
	s_waitcnt lgkmcnt(0)
	v_mfma_f32_16x16x32_bf16 v[74:77], v[174:177], v[142:145], v[74:77]
	ds_read_b128 v[174:177], v158
	s_waitcnt lgkmcnt(0)
	v_mfma_f32_16x16x32_bf16 v[70:73], v[174:177], v[130:133], v[70:73]
	ds_read_b128 v[174:177], v158 offset:64
	s_waitcnt lgkmcnt(0)
	v_mfma_f32_16x16x32_bf16 v[70:73], v[174:177], v[134:137], v[70:73]
	ds_read_b128 v[174:177], v158 offset:128
	s_waitcnt lgkmcnt(0)
	v_mfma_f32_16x16x32_bf16 v[70:73], v[174:177], v[138:141], v[70:73]
	ds_read_b128 v[174:177], v158 offset:192
	s_waitcnt lgkmcnt(0)
	v_mfma_f32_16x16x32_bf16 v[70:73], v[174:177], v[142:145], v[70:73]
	ds_read_b128 v[174:177], v157
	s_waitcnt lgkmcnt(0)
	v_mfma_f32_16x16x32_bf16 v[66:69], v[174:177], v[130:133], v[66:69]
	ds_read_b128 v[130:133], v157 offset:64
	s_waitcnt lgkmcnt(0)
	v_mfma_f32_16x16x32_bf16 v[66:69], v[130:133], v[134:137], v[66:69]
	ds_read_b128 v[130:133], v157 offset:128
	s_waitcnt lgkmcnt(0)
	v_mfma_f32_16x16x32_bf16 v[66:69], v[130:133], v[138:141], v[66:69]
	ds_read_b128 v[130:133], v157 offset:192
	s_waitcnt lgkmcnt(0)
	v_mfma_f32_16x16x32_bf16 v[66:69], v[130:133], v[142:145], v[66:69]
	global_load_dwordx4 v[130:133], v[202:203], off offset:256
	s_waitcnt vmcnt(0)
; #define LAS __attribute__((address_space(3)))
; __device__ __forceinline__ unsigned pk2(float lo, float hi) { const f32x2 v = {lo, hi}; return __builtin_bit_cast(unsigned, __builtin_convertvector(v, bf16x2_t)); }
; __device__ __forceinline__ f32x4 mfma16(bf16x8 a, bf16x8 b, f32x4 c) { return __builtin_amdgcn_mfma_f32_16x16x32_bf16(a, b, c, 0, 0, 0); }
; __device__ __forceinline__ void ret_out(const bf16* proj, const bf16* ST, bf16* mixed, const float* dexp, LAS unsigned char* lds, int vb, int nb, int tid_in0, int wave) {
;     ...
;                     for (int k4 = 0; k4 < 4; ++k4) { const int ks = 4 * kh + k4; const v4u q = *(const v4u*)(proj + (size_t)qrow * NIN + C_RQ + h * 256 + ks * 32 + g * 8); v4u r;
;                         r.x = pk2(bflo(q.x) * xi, bfhi(q.x) * xi); r.y = pk2(bflo(q.y) * xi, bfhi(q.y) * xi); r.z = pk2(bflo(q.z) * xi, bfhi(q.z) * xi); r.w = pk2(bflo(q.w) * xi, bfhi(q.w) * xi);
;                         qs[k4] = __builtin_bit_cast(bf16x8, r); }
; #pragma unroll
;                     for (int v = 0; v < 16; ++v) {
;                         const LAS unsigned char* sp = Sx + (v * 16 + qi) * 528 + g * 16 + kh * 256;
; #pragma unroll
;                         for (int k4 = 0; k4 < 4; ++k4) o[v] = mfma16(*(const LAS bf16x8*)(sp + k4 * 64), qs[k4], o[v]);
;                         if ((v & 1) == 1) asm volatile("" ::: "memory");
	v_lshlrev_b32_e32 v134, 16, v130
	v_and_b32_e32 v135, 0xffff0000, v130
	v_pk_mul_f32 v[134:135], v[146:147], v[134:135] op_sel_hi:[0,1]
	v_cvt_pk_bf16_f32 v130, v134, v135
	v_lshlrev_b32_e32 v134, 16, v131
	v_and_b32_e32 v135, 0xffff0000, v131
	v_pk_mul_f32 v[134:135], v[146:147], v[134:135] op_sel_hi:[0,1]
	v_cvt_pk_bf16_f32 v131, v134, v135
	v_lshlrev_b32_e32 v134, 16, v132
	v_and_b32_e32 v135, 0xffff0000, v132
	v_pk_mul_f32 v[134:135], v[146:147], v[134:135] op_sel_hi:[0,1]
	v_cvt_pk_bf16_f32 v132, v134, v135
	v_lshlrev_b32_e32 v134, 16, v133
	v_and_b32_e32 v135, 0xffff0000, v133
	v_pk_mul_f32 v[134:135], v[146:147], v[134:135] op_sel_hi:[0,1]
	v_cvt_pk_bf16_f32 v133, v134, v135
	global_load_dwordx4 v[134:137], v[202:203], off offset:320
	s_waitcnt vmcnt(0)
	v_lshlrev_b32_e32 v138, 16, v134
	v_and_b32_e32 v139, 0xffff0000, v134
	v_pk_mul_f32 v[138:139], v[146:147], v[138:139] op_sel_hi:[0,1]
	v_cvt_pk_bf16_f32 v134, v138, v139
	v_lshlrev_b32_e32 v138, 16, v135
	v_and_b32_e32 v139, 0xffff0000, v135
	v_pk_mul_f32 v[138:139], v[146:147], v[138:139] op_sel_hi:[0,1]
	v_cvt_pk_bf16_f32 v135, v138, v139
	v_lshlrev_b32_e32 v138, 16, v136
	v_and_b32_e32 v139, 0xffff0000, v136
	v_pk_mul_f32 v[138:139], v[146:147], v[138:139] op_sel_hi:[0,1]
	v_cvt_pk_bf16_f32 v136, v138, v139
	v_lshlrev_b32_e32 v138, 16, v137
	v_and_b32_e32 v139, 0xffff0000, v137
	v_pk_mul_f32 v[138:139], v[146:147], v[138:139] op_sel_hi:[0,1]
	v_cvt_pk_bf16_f32 v137, v138, v139
	global_load_dwordx4 v[138:141], v[202:203], off offset:384
	s_waitcnt vmcnt(0)
	v_lshlrev_b32_e32 v142, 16, v138
	v_and_b32_e32 v143, 0xffff0000, v138
	v_pk_mul_f32 v[142:143], v[146:147], v[142:143] op_sel_hi:[0,1]
	v_cvt_pk_bf16_f32 v138, v142, v143
	v_lshlrev_b32_e32 v142, 16, v139
	v_and_b32_e32 v143, 0xffff0000, v139
	v_pk_mul_f32 v[142:143], v[146:147], v[142:143] op_sel_hi:[0,1]
	v_cvt_pk_bf16_f32 v139, v142, v143
	v_lshlrev_b32_e32 v142, 16, v140
	v_and_b32_e32 v143, 0xffff0000, v140
	v_pk_mul_f32 v[142:143], v[146:147], v[142:143] op_sel_hi:[0,1]
	v_cvt_pk_bf16_f32 v140, v142, v143
	v_lshlrev_b32_e32 v142, 16, v141
	v_and_b32_e32 v143, 0xffff0000, v141
	v_pk_mul_f32 v[142:143], v[146:147], v[142:143] op_sel_hi:[0,1]
	v_cvt_pk_bf16_f32 v141, v142, v143
	global_load_dwordx4 v[142:145], v[202:203], off offset:448
	s_waitcnt vmcnt(0)
	v_lshlrev_b32_e32 v174, 16, v142
	v_and_b32_e32 v175, 0xffff0000, v142
	v_pk_mul_f32 v[174:175], v[146:147], v[174:175] op_sel_hi:[0,1]
	v_cvt_pk_bf16_f32 v142, v174, v175
	v_lshlrev_b32_e32 v174, 16, v143
	v_and_b32_e32 v175, 0xffff0000, v143
	v_pk_mul_f32 v[174:175], v[146:147], v[174:175] op_sel_hi:[0,1]
	v_cvt_pk_bf16_f32 v143, v174, v175
	v_lshlrev_b32_e32 v174, 16, v144
	v_and_b32_e32 v175, 0xffff0000, v144
	v_pk_mul_f32 v[174:175], v[146:147], v[174:175] op_sel_hi:[0,1]
	v_cvt_pk_bf16_f32 v144, v174, v175
	v_lshlrev_b32_e32 v174, 16, v145
	v_and_b32_e32 v175, 0xffff0000, v145
	v_pk_mul_f32 v[174:175], v[146:147], v[174:175] op_sel_hi:[0,1]
	v_cvt_pk_bf16_f32 v145, v174, v175
	ds_read_b128 v[174:177], v156 offset:256
	s_waitcnt lgkmcnt(0)
	v_mfma_f32_16x16x32_bf16 v[122:125], v[174:177], v[130:133], v[122:125]
	ds_read_b128 v[174:177], v156 offset:320
	v_add_u32_e32 v146, v148, v155
	s_waitcnt lgkmcnt(0)
	v_mfma_f32_16x16x32_bf16 v[122:125], v[174:177], v[134:137], v[122:125]
	ds_read_b128 v[174:177], v156 offset:384
	s_waitcnt lgkmcnt(0)
	v_mfma_f32_16x16x32_bf16 v[122:125], v[174:177], v[138:141], v[122:125]
	ds_read_b128 v[174:177], v156 offset:448
	s_waitcnt lgkmcnt(0)
	v_mfma_f32_16x16x32_bf16 v[122:125], v[174:177], v[142:145], v[122:125]
	ds_read_b128 v[174:177], v156 offset:8896
	ds_read_b128 v[178:181], v156 offset:8832
	ds_read_b128 v[232:235], v156 offset:8768
	ds_read_b128 v[236:239], v156 offset:8704
	s_waitcnt lgkmcnt(0)
	v_mfma_f32_16x16x32_bf16 v[126:129], v[236:239], v[130:133], v[126:129]
	v_mfma_f32_16x16x32_bf16 v[126:129], v[232:235], v[134:137], v[126:129]
	v_mfma_f32_16x16x32_bf16 v[126:129], v[178:181], v[138:141], v[126:129]
	v_mfma_f32_16x16x32_bf16 v[126:129], v[174:177], v[142:145], v[126:129]
	ds_read_b128 v[174:177], v156 offset:17152
	s_waitcnt lgkmcnt(0)
	v_mfma_f32_16x16x32_bf16 v[118:121], v[174:177], v[130:133], v[118:121]
	ds_read_b128 v[174:177], v156 offset:17216
	s_waitcnt lgkmcnt(0)
	v_mfma_f32_16x16x32_bf16 v[118:121], v[174:177], v[134:137], v[118:121]
	ds_read_b128 v[174:177], v156 offset:17280
	s_waitcnt lgkmcnt(0)
	v_mfma_f32_16x16x32_bf16 v[118:121], v[174:177], v[138:141], v[118:121]
	ds_read_b128 v[174:177], v156 offset:17344
	s_waitcnt lgkmcnt(0)
	v_mfma_f32_16x16x32_bf16 v[118:121], v[174:177], v[142:145], v[118:121]
	ds_read_b128 v[174:177], v156 offset:25792
	ds_read_b128 v[178:181], v156 offset:25728
	ds_read_b128 v[232:235], v156 offset:25664
	ds_read_b128 v[236:239], v156 offset:25600
	s_waitcnt lgkmcnt(0)
	v_mfma_f32_16x16x32_bf16 v[114:117], v[236:239], v[130:133], v[114:117]
	v_mfma_f32_16x16x32_bf16 v[114:117], v[232:235], v[134:137], v[114:117]
	v_mfma_f32_16x16x32_bf16 v[114:117], v[178:181], v[138:141], v[114:117]
	v_mfma_f32_16x16x32_bf16 v[114:117], v[174:177], v[142:145], v[114:117]
	ds_read_b128 v[174:177], v156 offset:34048
	s_waitcnt lgkmcnt(0)
	v_mfma_f32_16x16x32_bf16 v[110:113], v[174:177], v[130:133], v[110:113]
	ds_read_b128 v[174:177], v156 offset:34112
	s_waitcnt lgkmcnt(0)
	v_mfma_f32_16x16x32_bf16 v[110:113], v[174:177], v[134:137], v[110:113]
	ds_read_b128 v[174:177], v156 offset:34176
	s_waitcnt lgkmcnt(0)
	v_mfma_f32_16x16x32_bf16 v[110:113], v[174:177], v[138:141], v[110:113]
	ds_read_b128 v[174:177], v156 offset:34240
	s_waitcnt lgkmcnt(0)
; #define LAS __attribute__((address_space(3)))
; __device__ __forceinline__ f32x4 mfma16(bf16x8 a, bf16x8 b, f32x4 c) { return __builtin_amdgcn_mfma_f32_16x16x32_bf16(a, b, c, 0, 0, 0); }
; __device__ __forceinline__ void ret_out(const bf16* proj, const bf16* ST, bf16* mixed, const float* dexp, LAS unsigned char* lds, int vb, int nb, int tid_in0, int wave) {
;     ...
; #pragma unroll
;                     for (int v = 0; v < 16; ++v) {
;                         const LAS unsigned char* sp = Sx + (v * 16 + qi) * 528 + g * 16 + kh * 256;
; #pragma unroll
;                         for (int k4 = 0; k4 < 4; ++k4) o[v] = mfma16(*(const LAS bf16x8*)(sp + k4 * 64), qs[k4], o[v]);
;                         if ((v & 1) == 1) asm volatile("" ::: "memory");
	v_mfma_f32_16x16x32_bf16 v[110:113], v[174:177], v[142:145], v[110:113]
	ds_read_b128 v[174:177], v156 offset:42688
	ds_read_b128 v[178:181], v156 offset:42624
	ds_read_b128 v[232:235], v156 offset:42560
	ds_read_b128 v[236:239], v156 offset:42496
	s_waitcnt lgkmcnt(0)
	v_mfma_f32_16x16x32_bf16 v[106:109], v[236:239], v[130:133], v[106:109]
	v_mfma_f32_16x16x32_bf16 v[106:109], v[232:235], v[134:137], v[106:109]
	v_mfma_f32_16x16x32_bf16 v[106:109], v[178:181], v[138:141], v[106:109]
	v_mfma_f32_16x16x32_bf16 v[106:109], v[174:177], v[142:145], v[106:109]
	ds_read_b128 v[174:177], v156 offset:50944
	s_waitcnt lgkmcnt(0)
	v_mfma_f32_16x16x32_bf16 v[102:105], v[174:177], v[130:133], v[102:105]
	ds_read_b128 v[174:177], v156 offset:51008
	s_waitcnt lgkmcnt(0)
	v_mfma_f32_16x16x32_bf16 v[102:105], v[174:177], v[134:137], v[102:105]
	ds_read_b128 v[174:177], v156 offset:51072
	s_waitcnt lgkmcnt(0)
	v_mfma_f32_16x16x32_bf16 v[102:105], v[174:177], v[138:141], v[102:105]
	ds_read_b128 v[174:177], v156 offset:51136
	s_waitcnt lgkmcnt(0)
	v_mfma_f32_16x16x32_bf16 v[102:105], v[174:177], v[142:145], v[102:105]
	ds_read_b128 v[174:177], v156 offset:59584
	ds_read_b128 v[178:181], v156 offset:59520
	ds_read_b128 v[232:235], v156 offset:59456
	ds_read_b128 v[236:239], v156 offset:59392
	s_waitcnt lgkmcnt(0)
	v_mfma_f32_16x16x32_bf16 v[98:101], v[236:239], v[130:133], v[98:101]
	v_mfma_f32_16x16x32_bf16 v[98:101], v[232:235], v[134:137], v[98:101]
	v_mfma_f32_16x16x32_bf16 v[98:101], v[178:181], v[138:141], v[98:101]
	v_mfma_f32_16x16x32_bf16 v[98:101], v[174:177], v[142:145], v[98:101]
	ds_read_b128 v[174:177], v146
	s_waitcnt lgkmcnt(0)
	v_mfma_f32_16x16x32_bf16 v[94:97], v[174:177], v[130:133], v[94:97]
	ds_read_b128 v[174:177], v146 offset:64
	s_waitcnt lgkmcnt(0)
	v_mfma_f32_16x16x32_bf16 v[94:97], v[174:177], v[134:137], v[94:97]
	ds_read_b128 v[174:177], v146 offset:128
	s_waitcnt lgkmcnt(0)
	v_mfma_f32_16x16x32_bf16 v[94:97], v[174:177], v[138:141], v[94:97]
	ds_read_b128 v[174:177], v146 offset:192
	v_add_u32_e32 v146, v148, v154
	s_waitcnt lgkmcnt(0)
	v_mfma_f32_16x16x32_bf16 v[94:97], v[174:177], v[142:145], v[94:97]
	ds_read_b128 v[174:177], v146 offset:192
	ds_read_b128 v[178:181], v146 offset:128
	ds_read_b128 v[232:235], v146 offset:64
	ds_read_b128 v[236:239], v146
	v_add_u32_e32 v146, v148, v153
	s_waitcnt lgkmcnt(0)
	v_mfma_f32_16x16x32_bf16 v[90:93], v[236:239], v[130:133], v[90:93]
	v_mfma_f32_16x16x32_bf16 v[90:93], v[232:235], v[134:137], v[90:93]
	v_mfma_f32_16x16x32_bf16 v[90:93], v[178:181], v[138:141], v[90:93]
	v_mfma_f32_16x16x32_bf16 v[90:93], v[174:177], v[142:145], v[90:93]
	ds_read_b128 v[174:177], v146
	s_waitcnt lgkmcnt(0)
	v_mfma_f32_16x16x32_bf16 v[86:89], v[174:177], v[130:133], v[86:89]
	ds_read_b128 v[174:177], v146 offset:64
	s_waitcnt lgkmcnt(0)
	v_mfma_f32_16x16x32_bf16 v[86:89], v[174:177], v[134:137], v[86:89]
	ds_read_b128 v[174:177], v146 offset:128
	s_waitcnt lgkmcnt(0)
	v_mfma_f32_16x16x32_bf16 v[86:89], v[174:177], v[138:141], v[86:89]
	ds_read_b128 v[174:177], v146 offset:192
	v_add_u32_e32 v146, v148, v152
	s_waitcnt lgkmcnt(0)
	v_mfma_f32_16x16x32_bf16 v[86:89], v[174:177], v[142:145], v[86:89]
	ds_read_b128 v[174:177], v146 offset:192
	ds_read_b128 v[178:181], v146 offset:128
	ds_read_b128 v[232:235], v146 offset:64
	ds_read_b128 v[236:239], v146
	v_add_u32_e32 v146, v148, v151
	s_waitcnt lgkmcnt(0)
	v_mfma_f32_16x16x32_bf16 v[82:85], v[236:239], v[130:133], v[82:85]
	v_mfma_f32_16x16x32_bf16 v[82:85], v[232:235], v[134:137], v[82:85]
	v_mfma_f32_16x16x32_bf16 v[82:85], v[178:181], v[138:141], v[82:85]
	v_mfma_f32_16x16x32_bf16 v[82:85], v[174:177], v[142:145], v[82:85]
	ds_read_b128 v[174:177], v146
	s_waitcnt lgkmcnt(0)
	v_mfma_f32_16x16x32_bf16 v[78:81], v[174:177], v[130:133], v[78:81]
	ds_read_b128 v[174:177], v146 offset:64
	s_waitcnt lgkmcnt(0)
	v_mfma_f32_16x16x32_bf16 v[78:81], v[174:177], v[134:137], v[78:81]
	ds_read_b128 v[174:177], v146 offset:128
	s_waitcnt lgkmcnt(0)
	v_mfma_f32_16x16x32_bf16 v[78:81], v[174:177], v[138:141], v[78:81]
	ds_read_b128 v[174:177], v146 offset:192
	v_add_u32_e32 v146, v148, v150
	s_waitcnt lgkmcnt(0)
	v_mfma_f32_16x16x32_bf16 v[78:81], v[174:177], v[142:145], v[78:81]
	ds_read_b128 v[174:177], v146 offset:192
	ds_read_b128 v[178:181], v146 offset:128
	ds_read_b128 v[232:235], v146 offset:64
	ds_read_b128 v[236:239], v146
	v_add_u32_e32 v146, v148, v149
	s_waitcnt lgkmcnt(0)
	v_mfma_f32_16x16x32_bf16 v[74:77], v[236:239], v[130:133], v[74:77]
	v_mfma_f32_16x16x32_bf16 v[74:77], v[232:235], v[134:137], v[74:77]
	v_mfma_f32_16x16x32_bf16 v[74:77], v[178:181], v[138:141], v[74:77]
	v_mfma_f32_16x16x32_bf16 v[74:77], v[174:177], v[142:145], v[74:77]
	ds_read_b128 v[174:177], v146
	s_waitcnt lgkmcnt(0)
	v_mfma_f32_16x16x32_bf16 v[70:73], v[174:177], v[130:133], v[70:73]
	ds_read_b128 v[174:177], v146 offset:64
	s_waitcnt lgkmcnt(0)
	v_mfma_f32_16x16x32_bf16 v[70:73], v[174:177], v[134:137], v[70:73]
	ds_read_b128 v[174:177], v146 offset:128
	s_waitcnt lgkmcnt(0)
	v_mfma_f32_16x16x32_bf16 v[70:73], v[174:177], v[138:141], v[70:73]
	ds_read_b128 v[174:177], v146 offset:192
	v_add_u32_e32 v146, v148, v147
	s_waitcnt lgkmcnt(0)
	v_mfma_f32_16x16x32_bf16 v[70:73], v[174:177], v[142:145], v[70:73]
	ds_read_b128 v[174:177], v146 offset:192
	ds_read_b128 v[178:181], v146 offset:128
	ds_read_b128 v[232:235], v146 offset:64
	ds_read_b128 v[236:239], v146
	s_waitcnt lgkmcnt(0)
	v_mfma_f32_16x16x32_bf16 v[66:69], v[236:239], v[130:133], v[66:69]
	v_mfma_f32_16x16x32_bf16 v[66:69], v[232:235], v[134:137], v[66:69]
	v_mfma_f32_16x16x32_bf16 v[66:69], v[178:181], v[138:141], v[66:69]
	v_mfma_f32_16x16x32_bf16 v[66:69], v[174:177], v[142:145], v[66:69]

; __device__ __forceinline__ unsigned pk2(float lo, float hi) { const f32x2 v = {lo, hi}; return __builtin_bit_cast(unsigned, __builtin_convertvector(v, bf16x2_t)); }
; __device__ __forceinline__ void ret_out(const bf16* proj, const bf16* ST, bf16* mixed, const float* dexp, LAS unsigned char* lds, int vb, int nb, int tid_in0, int wave) {
;     ...
;             else { const int un = unit + nb;
;                 if (un < 1536) { const int gc2 = un >> 3, h2 = un & 7, rowb2 = gc2 * 128;
; #pragma unroll
;                     for (int i = 0; i < 8; ++i) { const int id = tid + 512 * i, j = id >> 5, ch = id & 31;
;                         pf[i] = *(const v4u*)(proj + (size_t)(rowb2 + j) * NIN + C_RK + h2 * 256 + ch * 8); pf[8 + i] = *(const v4u*)(proj + (size_t)(rowb2 + j) * NIN + C_RV + h2 * 256 + ch * 8); } } }
;             if (have) {
;                 const float xi = dir == 0 ? __expf(lgf * (float)(iq + 1)) : __expf(lgb * (float)(128 - iq));
; #pragma unroll
;                 for (int kh = 0; kh < 2; ++kh) {
;                     bf16x8 qs[4];
; #pragma unroll
;                     for (int k4 = 0; k4 < 4; ++k4) { const int ks = 4 * kh + k4; const v4u q = *(const v4u*)(proj + (size_t)qrow * NIN + C_RQ + h * 256 + ks * 32 + g * 8); v4u r;
;                         r.x = pk2(bflo(q.x) * xi, bfhi(q.x) * xi); r.y = pk2(bflo(q.y) * xi, bfhi(q.y) * xi); r.z = pk2(bflo(q.z) * xi, bfhi(q.z) * xi); r.w = pk2(bflo(q.w) * xi, bfhi(q.w) * xi);
.LBB0_846:
	s_add_i32 s14, s14, s10
	s_cmpk_gt_i32 s14, 0x5ff
	s_cselect_b64 s[6:7], -1, 0
	s_and_b64 vcc, exec, s[6:7]
	s_waitcnt lgkmcnt(0)
	s_barrier
	s_cbranch_vccnz .LBB0_848
	s_andn2_b64 vcc, exec, s[4:5]
	s_cbranch_vccnz .LBB0_848
	s_and_b32 s15, s64, 0xffffff80
	s_and_b32 s28, s11, 0x700
	s_waitcnt vmcnt(15)
	v_add_u32_e32 v2, s15, v208
	s_waitcnt vmcnt(8)
	v_mov_b64_e32 v[46:47], s[36:37]
	v_mad_i64_i32 v[2:3], s[26:27], v2, s33, v[46:47]
	s_lshl_b32 s62, s28, 1
	v_lshlrev_b64 v[48:49], 1, v[182:183]
	v_lshl_add_u64 v[2:3], v[2:3], 0, s[62:63]
	v_lshl_add_u64 v[2:3], v[2:3], 0, v[48:49]
	v_add_co_u32_e32 v4, vcc, 0x4000, v2
	s_waitcnt vmcnt(0)
	v_add_u32_e32 v62, s15, v190
	v_addc_co_u32_e32 v5, vcc, 0, v3, vcc
	v_add_co_u32_e32 v6, vcc, 0x5000, v2
	s_nop 1
	v_addc_co_u32_e32 v7, vcc, 0, v3, vcc
	global_load_dwordx4 v[2:5], v[4:5], off
	s_nop 0
	global_load_dwordx4 v[18:21], v[6:7], off
	v_add_u32_e32 v6, s15, v207
	v_mad_i64_i32 v[6:7], s[26:27], v6, s33, v[46:47]
	v_lshl_add_u64 v[6:7], v[6:7], 0, s[62:63]
	v_lshl_add_u64 v[6:7], v[6:7], 0, v[48:49]
	v_add_co_u32_e32 v8, vcc, 0x4000, v6
	s_nop 1
	v_addc_co_u32_e32 v9, vcc, 0, v7, vcc
	v_add_co_u32_e32 v10, vcc, 0x5000, v6
	s_nop 1
	v_addc_co_u32_e32 v11, vcc, 0, v7, vcc
	global_load_dwordx4 v[6:9], v[8:9], off
	s_nop 0
	global_load_dwordx4 v[22:25], v[10:11], off
	v_add_u32_e32 v10, s15, v206
	v_mad_i64_i32 v[10:11], s[26:27], v10, s33, v[46:47]
	v_lshl_add_u64 v[10:11], v[10:11], 0, s[62:63]
	v_lshl_add_u64 v[10:11], v[10:11], 0, v[48:49]
	v_add_co_u32_e32 v12, vcc, 0x4000, v10
	s_nop 1
	v_addc_co_u32_e32 v13, vcc, 0, v11, vcc
	v_add_co_u32_e32 v14, vcc, 0x5000, v10
	s_nop 1
	v_addc_co_u32_e32 v15, vcc, 0, v11, vcc
	global_load_dwordx4 v[10:13], v[12:13], off
	s_nop 0
	global_load_dwordx4 v[34:37], v[14:15], off
	v_add_u32_e32 v14, s15, v205
	v_mad_i64_i32 v[14:15], s[26:27], v14, s33, v[46:47]
	v_lshl_add_u64 v[14:15], v[14:15], 0, s[62:63]
	v_lshl_add_u64 v[14:15], v[14:15], 0, v[48:49]
	v_add_co_u32_e32 v16, vcc, 0x4000, v14
	s_nop 1
	v_addc_co_u32_e32 v17, vcc, 0, v15, vcc
	v_add_co_u32_e32 v26, vcc, 0x5000, v14
	s_nop 1
	v_addc_co_u32_e32 v27, vcc, 0, v15, vcc
	global_load_dwordx4 v[14:17], v[16:17], off
	s_nop 0
	global_load_dwordx4 v[38:41], v[26:27], off
	v_add_u32_e32 v26, s15, v204
	v_mad_i64_i32 v[26:27], s[26:27], v26, s33, v[46:47]
	v_lshl_add_u64 v[26:27], v[26:27], 0, s[62:63]
	v_lshl_add_u64 v[26:27], v[26:27], 0, v[48:49]
	v_add_co_u32_e32 v28, vcc, 0x4000, v26
	s_nop 1
	v_addc_co_u32_e32 v29, vcc, 0, v27, vcc
	v_add_co_u32_e32 v30, vcc, 0x5000, v26
	s_nop 1
	v_addc_co_u32_e32 v31, vcc, 0, v27, vcc
	global_load_dwordx4 v[26:29], v[28:29], off
	s_nop 0
	global_load_dwordx4 v[50:53], v[30:31], off
	v_add_u32_e32 v30, s15, v199
	v_mad_i64_i32 v[30:31], s[26:27], v30, s33, v[46:47]
	v_lshl_add_u64 v[30:31], v[30:31], 0, s[62:63]
	v_lshl_add_u64 v[30:31], v[30:31], 0, v[48:49]
	v_add_co_u32_e32 v32, vcc, 0x4000, v30
	s_nop 1
	v_addc_co_u32_e32 v33, vcc, 0, v31, vcc
	v_add_co_u32_e32 v42, vcc, 0x5000, v30
	s_nop 1
	v_addc_co_u32_e32 v43, vcc, 0, v31, vcc
	global_load_dwordx4 v[30:33], v[32:33], off
	s_nop 0
	global_load_dwordx4 v[54:57], v[42:43], off
	v_add_u32_e32 v42, s15, v192
	v_mad_i64_i32 v[42:43], s[26:27], v42, s33, v[46:47]
	v_lshl_add_u64 v[42:43], v[42:43], 0, s[62:63]
	v_lshl_add_u64 v[42:43], v[42:43], 0, v[48:49]
	v_add_co_u32_e32 v44, vcc, 0x4000, v42
	v_mad_i64_i32 v[46:47], s[26:27], v62, s33, v[46:47]
	s_nop 0
	v_addc_co_u32_e32 v45, vcc, 0, v43, vcc
	v_add_co_u32_e32 v58, vcc, 0x5000, v42
	v_lshl_add_u64 v[46:47], v[46:47], 0, s[62:63]
	s_nop 0
	v_addc_co_u32_e32 v59, vcc, 0, v43, vcc
	v_lshl_add_u64 v[46:47], v[46:47], 0, v[48:49]
	v_add_co_u32_e32 v48, vcc, 0x4000, v46
	global_load_dwordx4 v[42:45], v[44:45], off
	s_nop 0
	global_load_dwordx4 v[58:61], v[58:59], off
	v_addc_co_u32_e32 v49, vcc, 0, v47, vcc
	v_add_co_u32_e32 v62, vcc, 0x5000, v46
	s_nop 1
	v_addc_co_u32_e32 v63, vcc, 0, v47, vcc
	global_load_dwordx4 v[46:49], v[48:49], off
	s_nop 0
	global_load_dwordx4 v[62:65], v[62:63], off
.LBB0_848:
	s_and_b64 vcc, exec, s[4:5]
	s_lshl_b32 s4, s66, 8
	s_cbranch_vccnz .LBB0_833
	v_sub_u32_e32 v130, 0x80, v189
	v_cvt_f32_i32_e32 v130, v130
	v_mul_f32_e32 v130, v230, v130
	v_mul_f32_e32 v130, 0x3fb8aa3b, v130
	v_exp_f32_e32 v146, v130
	global_load_dwordx4 v[130:133], v[202:203], off
	s_waitcnt vmcnt(0)
	v_lshlrev_b32_e32 v134, 16, v130
	v_and_b32_e32 v135, 0xffff0000, v130
	v_pk_mul_f32 v[134:135], v[146:147], v[134:135] op_sel_hi:[0,1]
	v_cvt_pk_bf16_f32 v130, v134, v135
	v_lshlrev_b32_e32 v134, 16, v131
	v_and_b32_e32 v135, 0xffff0000, v131
	v_pk_mul_f32 v[134:135], v[146:147], v[134:135] op_sel_hi:[0,1]
	v_cvt_pk_bf16_f32 v131, v134, v135
	v_lshlrev_b32_e32 v134, 16, v132
	v_and_b32_e32 v135, 0xffff0000, v132
	v_pk_mul_f32 v[134:135], v[146:147], v[134:135] op_sel_hi:[0,1]
	v_cvt_pk_bf16_f32 v132, v134, v135
	v_lshlrev_b32_e32 v134, 16, v133
	v_and_b32_e32 v135, 0xffff0000, v133
	v_pk_mul_f32 v[134:135], v[146:147], v[134:135] op_sel_hi:[0,1]
	v_cvt_pk_bf16_f32 v133, v134, v135
	global_load_dwordx4 v[134:137], v[202:203], off offset:64
	s_waitcnt vmcnt(0)
	v_lshlrev_b32_e32 v138, 16, v134
	v_and_b32_e32 v139, 0xffff0000, v134
	v_pk_mul_f32 v[138:139], v[146:147], v[138:139] op_sel_hi:[0,1]
	v_cvt_pk_bf16_f32 v134, v138, v139
	v_lshlrev_b32_e32 v138, 16, v135
	v_and_b32_e32 v139, 0xffff0000, v135
	v_pk_mul_f32 v[138:139], v[146:147], v[138:139] op_sel_hi:[0,1]
	v_cvt_pk_bf16_f32 v135, v138, v139
	v_lshlrev_b32_e32 v138, 16, v136
	v_and_b32_e32 v139, 0xffff0000, v136
	v_pk_mul_f32 v[138:139], v[146:147], v[138:139] op_sel_hi:[0,1]
	v_cvt_pk_bf16_f32 v136, v138, v139
	v_lshlrev_b32_e32 v138, 16, v137
	v_and_b32_e32 v139, 0xffff0000, v137
	v_pk_mul_f32 v[138:139], v[146:147], v[138:139] op_sel_hi:[0,1]
	v_cvt_pk_bf16_f32 v137, v138, v139
	global_load_dwordx4 v[138:141], v[202:203], off offset:128
	s_waitcnt vmcnt(0)
; __device__ __forceinline__ unsigned pk2(float lo, float hi) { const f32x2 v = {lo, hi}; return __builtin_bit_cast(unsigned, __builtin_convertvector(v, bf16x2_t)); }
; __device__ __forceinline__ void ret_out(const bf16* proj, const bf16* ST, bf16* mixed, const float* dexp, LAS unsigned char* lds, int vb, int nb, int tid_in0, int wave) {
;     ...
;             else { const int un = unit + nb;
;                 if (un < 1536) { const int gc2 = un >> 3, h2 = un & 7, rowb2 = gc2 * 128;
; #pragma unroll
;                     for (int i = 0; i < 8; ++i) { const int id = tid + 512 * i, j = id >> 5, ch = id & 31;
;                         pf[i] = *(const v4u*)(proj + (size_t)(rowb2 + j) * NIN + C_RK + h2 * 256 + ch * 8); pf[8 + i] = *(const v4u*)(proj + (size_t)(rowb2 + j) * NIN + C_RV + h2 * 256 + ch * 8); } } }
;     ...
;                     for (int k4 = 0; k4 < 4; ++k4) { const int ks = 4 * kh + k4; const v4u q = *(const v4u*)(proj + (size_t)qrow * NIN + C_RQ + h * 256 + ks * 32 + g * 8); v4u r;
;                         r.x = pk2(bflo(q.x) * xi, bfhi(q.x) * xi); r.y = pk2(bflo(q.y) * xi, bfhi(q.y) * xi); r.z = pk2(bflo(q.z) * xi, bfhi(q.z) * xi); r.w = pk2(bflo(q.w) * xi, bfhi(q.w) * xi);
;                         qs[k4] = __builtin_bit_cast(bf16x8, r); }
	v_lshlrev_b32_e32 v142, 16, v138
	v_and_b32_e32 v143, 0xffff0000, v138
	v_pk_mul_f32 v[142:143], v[146:147], v[142:143] op_sel_hi:[0,1]
	v_cvt_pk_bf16_f32 v138, v142, v143
	v_lshlrev_b32_e32 v142, 16, v139
	v_and_b32_e32 v143, 0xffff0000, v139
	v_pk_mul_f32 v[142:143], v[146:147], v[142:143] op_sel_hi:[0,1]
	v_cvt_pk_bf16_f32 v139, v142, v143
	v_lshlrev_b32_e32 v142, 16, v140
	v_and_b32_e32 v143, 0xffff0000, v140
	v_pk_mul_f32 v[142:143], v[146:147], v[142:143] op_sel_hi:[0,1]
	v_cvt_pk_bf16_f32 v140, v142, v143
	v_lshlrev_b32_e32 v142, 16, v141
	v_and_b32_e32 v143, 0xffff0000, v141
	v_pk_mul_f32 v[142:143], v[146:147], v[142:143] op_sel_hi:[0,1]
	v_cvt_pk_bf16_f32 v141, v142, v143
	global_load_dwordx4 v[142:145], v[202:203], off offset:192
	s_waitcnt vmcnt(0)
	v_lshlrev_b32_e32 v166, 16, v142
	v_and_b32_e32 v167, 0xffff0000, v142
	v_pk_mul_f32 v[166:167], v[146:147], v[166:167] op_sel_hi:[0,1]
	v_cvt_pk_bf16_f32 v142, v166, v167
	v_lshlrev_b32_e32 v166, 16, v143
	v_and_b32_e32 v167, 0xffff0000, v143
	v_pk_mul_f32 v[166:167], v[146:147], v[166:167] op_sel_hi:[0,1]
	v_cvt_pk_bf16_f32 v143, v166, v167
	v_lshlrev_b32_e32 v166, 16, v144
	v_and_b32_e32 v167, 0xffff0000, v144
	v_pk_mul_f32 v[166:167], v[146:147], v[166:167] op_sel_hi:[0,1]
	v_cvt_pk_bf16_f32 v144, v166, v167
	v_lshlrev_b32_e32 v166, 16, v145
	v_and_b32_e32 v167, 0xffff0000, v145
	v_pk_mul_f32 v[166:167], v[146:147], v[166:167] op_sel_hi:[0,1]
	v_cvt_pk_bf16_f32 v145, v166, v167
	s_and_b64 vcc, exec, s[6:7]
	s_cbranch_vccnz .Lro_nopf_d1
	s_and_b32 s15, s64, 0xffffff80
	s_and_b32 s28, s11, 0x700
	s_waitcnt vmcnt(15)
	v_add_u32_e32 v2, s15, v208
	s_waitcnt vmcnt(8)
	v_mov_b64_e32 v[46:47], s[36:37]
	v_mad_i64_i32 v[2:3], s[26:27], v2, s33, v[46:47]
	s_lshl_b32 s62, s28, 1
	v_lshlrev_b64 v[48:49], 1, v[182:183]
	v_lshl_add_u64 v[2:3], v[2:3], 0, s[62:63]
	v_lshl_add_u64 v[2:3], v[2:3], 0, v[48:49]
	v_add_co_u32_e32 v4, vcc, 0x4000, v2
	s_waitcnt vmcnt(0)
	v_add_u32_e32 v62, s15, v190
	v_addc_co_u32_e32 v5, vcc, 0, v3, vcc
	v_add_co_u32_e32 v6, vcc, 0x5000, v2
	s_nop 1
	v_addc_co_u32_e32 v7, vcc, 0, v3, vcc
	global_load_dwordx4 v[2:5], v[4:5], off
	s_nop 0
	global_load_dwordx4 v[18:21], v[6:7], off
	v_add_u32_e32 v6, s15, v207
	v_mad_i64_i32 v[6:7], s[26:27], v6, s33, v[46:47]
	v_lshl_add_u64 v[6:7], v[6:7], 0, s[62:63]
	v_lshl_add_u64 v[6:7], v[6:7], 0, v[48:49]
	v_add_co_u32_e32 v8, vcc, 0x4000, v6
	s_nop 1
	v_addc_co_u32_e32 v9, vcc, 0, v7, vcc
	v_add_co_u32_e32 v10, vcc, 0x5000, v6
	s_nop 1
	v_addc_co_u32_e32 v11, vcc, 0, v7, vcc
	global_load_dwordx4 v[6:9], v[8:9], off
	s_nop 0
	global_load_dwordx4 v[22:25], v[10:11], off
	v_add_u32_e32 v10, s15, v206
	v_mad_i64_i32 v[10:11], s[26:27], v10, s33, v[46:47]
	v_lshl_add_u64 v[10:11], v[10:11], 0, s[62:63]
	v_lshl_add_u64 v[10:11], v[10:11], 0, v[48:49]
	v_add_co_u32_e32 v12, vcc, 0x4000, v10
	s_nop 1
	v_addc_co_u32_e32 v13, vcc, 0, v11, vcc
	v_add_co_u32_e32 v14, vcc, 0x5000, v10
	s_nop 1
	v_addc_co_u32_e32 v15, vcc, 0, v11, vcc
	global_load_dwordx4 v[10:13], v[12:13], off
	s_nop 0
	global_load_dwordx4 v[34:37], v[14:15], off
	v_add_u32_e32 v14, s15, v205
	v_mad_i64_i32 v[14:15], s[26:27], v14, s33, v[46:47]
	v_lshl_add_u64 v[14:15], v[14:15], 0, s[62:63]
	v_lshl_add_u64 v[14:15], v[14:15], 0, v[48:49]
	v_add_co_u32_e32 v16, vcc, 0x4000, v14
	s_nop 1
	v_addc_co_u32_e32 v17, vcc, 0, v15, vcc
	v_add_co_u32_e32 v26, vcc, 0x5000, v14
	s_nop 1
	v_addc_co_u32_e32 v27, vcc, 0, v15, vcc
	global_load_dwordx4 v[14:17], v[16:17], off
	s_nop 0
	global_load_dwordx4 v[38:41], v[26:27], off
	v_add_u32_e32 v26, s15, v204
	v_mad_i64_i32 v[26:27], s[26:27], v26, s33, v[46:47]
	v_lshl_add_u64 v[26:27], v[26:27], 0, s[62:63]
	v_lshl_add_u64 v[26:27], v[26:27], 0, v[48:49]
	v_add_co_u32_e32 v28, vcc, 0x4000, v26
	s_nop 1
	v_addc_co_u32_e32 v29, vcc, 0, v27, vcc
	v_add_co_u32_e32 v30, vcc, 0x5000, v26
	s_nop 1
	v_addc_co_u32_e32 v31, vcc, 0, v27, vcc
	global_load_dwordx4 v[26:29], v[28:29], off
	s_nop 0
	global_load_dwordx4 v[50:53], v[30:31], off
	v_add_u32_e32 v30, s15, v199
	v_mad_i64_i32 v[30:31], s[26:27], v30, s33, v[46:47]
	v_lshl_add_u64 v[30:31], v[30:31], 0, s[62:63]
	v_lshl_add_u64 v[30:31], v[30:31], 0, v[48:49]
	v_add_co_u32_e32 v32, vcc, 0x4000, v30
	s_nop 1
	v_addc_co_u32_e32 v33, vcc, 0, v31, vcc
	v_add_co_u32_e32 v42, vcc, 0x5000, v30
	s_nop 1
	v_addc_co_u32_e32 v43, vcc, 0, v31, vcc
	global_load_dwordx4 v[30:33], v[32:33], off
	s_nop 0
	global_load_dwordx4 v[54:57], v[42:43], off
	v_add_u32_e32 v42, s15, v192
	v_mad_i64_i32 v[42:43], s[26:27], v42, s33, v[46:47]
	v_lshl_add_u64 v[42:43], v[42:43], 0, s[62:63]
	v_lshl_add_u64 v[42:43], v[42:43], 0, v[48:49]
	v_add_co_u32_e32 v44, vcc, 0x4000, v42
	v_mad_i64_i32 v[46:47], s[26:27], v62, s33, v[46:47]
	s_nop 0
	v_addc_co_u32_e32 v45, vcc, 0, v43, vcc
	v_add_co_u32_e32 v58, vcc, 0x5000, v42
	v_lshl_add_u64 v[46:47], v[46:47], 0, s[62:63]
	s_nop 0
	v_addc_co_u32_e32 v59, vcc, 0, v43, vcc
	v_lshl_add_u64 v[46:47], v[46:47], 0, v[48:49]
	v_add_co_u32_e32 v48, vcc, 0x4000, v46
	global_load_dwordx4 v[42:45], v[44:45], off
	s_nop 0
	global_load_dwordx4 v[58:61], v[58:59], off
	v_addc_co_u32_e32 v49, vcc, 0, v47, vcc
	v_add_co_u32_e32 v62, vcc, 0x5000, v46
	s_nop 1
	v_addc_co_u32_e32 v63, vcc, 0, v47, vcc
	global_load_dwordx4 v[46:49], v[48:49], off
	s_nop 0
	global_load_dwordx4 v[62:65], v[62:63], off
; #define LAS __attribute__((address_space(3)))
; __device__ __forceinline__ f32x4 mfma16(bf16x8 a, bf16x8 b, f32x4 c) { return __builtin_amdgcn_mfma_f32_16x16x32_bf16(a, b, c, 0, 0, 0); }
; __device__ __forceinline__ void ret_out(const bf16* proj, const bf16* ST, bf16* mixed, const float* dexp, LAS unsigned char* lds, int vb, int nb, int tid_in0, int wave) {
;     ...
; #pragma unroll
;                     for (int v = 0; v < 16; ++v) {
;                         const LAS unsigned char* sp = Sx + (v * 16 + qi) * 528 + g * 16 + kh * 256;
; #pragma unroll
;                         for (int k4 = 0; k4 < 4; ++k4) o[v] = mfma16(*(const LAS bf16x8*)(sp + k4 * 64), qs[k4], o[v]);
;                         if ((v & 1) == 1) asm volatile("" ::: "memory");
;                     }
.Lro_nopf_d1:
	ds_read_b128 v[166:169], v156
	s_waitcnt lgkmcnt(0)
	v_mfma_f32_16x16x32_bf16 v[122:125], v[166:169], v[130:133], v[122:125]
	ds_read_b128 v[166:169], v156 offset:64
	s_waitcnt lgkmcnt(0)
	v_mfma_f32_16x16x32_bf16 v[122:125], v[166:169], v[134:137], v[122:125]
	ds_read_b128 v[166:169], v156 offset:128
	s_waitcnt lgkmcnt(0)
	v_mfma_f32_16x16x32_bf16 v[122:125], v[166:169], v[138:141], v[122:125]
	ds_read_b128 v[166:169], v156 offset:192
	s_waitcnt lgkmcnt(0)
	v_mfma_f32_16x16x32_bf16 v[122:125], v[166:169], v[142:145], v[122:125]
	ds_read_b128 v[166:169], v156 offset:8640
	ds_read_b128 v[170:173], v156 offset:8576
	ds_read_b128 v[174:177], v156 offset:8512
	ds_read_b128 v[178:181], v156 offset:8448
	s_waitcnt lgkmcnt(0)
	v_mfma_f32_16x16x32_bf16 v[126:129], v[178:181], v[130:133], v[126:129]
	v_mfma_f32_16x16x32_bf16 v[126:129], v[174:177], v[134:137], v[126:129]
	v_mfma_f32_16x16x32_bf16 v[126:129], v[170:173], v[138:141], v[126:129]
	v_mfma_f32_16x16x32_bf16 v[126:129], v[166:169], v[142:145], v[126:129]
	ds_read_b128 v[166:169], v156 offset:16896
	s_waitcnt lgkmcnt(0)
	v_mfma_f32_16x16x32_bf16 v[118:121], v[166:169], v[130:133], v[118:121]
	ds_read_b128 v[166:169], v156 offset:16960
	s_waitcnt lgkmcnt(0)
	v_mfma_f32_16x16x32_bf16 v[118:121], v[166:169], v[134:137], v[118:121]
	ds_read_b128 v[166:169], v156 offset:17024
	s_waitcnt lgkmcnt(0)
	v_mfma_f32_16x16x32_bf16 v[118:121], v[166:169], v[138:141], v[118:121]
	ds_read_b128 v[166:169], v156 offset:17088
	s_waitcnt lgkmcnt(0)
	v_mfma_f32_16x16x32_bf16 v[118:121], v[166:169], v[142:145], v[118:121]
	ds_read_b128 v[166:169], v156 offset:25536
	ds_read_b128 v[170:173], v156 offset:25472
	ds_read_b128 v[174:177], v156 offset:25408
	ds_read_b128 v[178:181], v156 offset:25344
	s_waitcnt lgkmcnt(0)
	v_mfma_f32_16x16x32_bf16 v[114:117], v[178:181], v[130:133], v[114:117]
	v_mfma_f32_16x16x32_bf16 v[114:117], v[174:177], v[134:137], v[114:117]
	v_mfma_f32_16x16x32_bf16 v[114:117], v[170:173], v[138:141], v[114:117]
	v_mfma_f32_16x16x32_bf16 v[114:117], v[166:169], v[142:145], v[114:117]
	ds_read_b128 v[166:169], v156 offset:33792
	s_waitcnt lgkmcnt(0)
	v_mfma_f32_16x16x32_bf16 v[110:113], v[166:169], v[130:133], v[110:113]
	ds_read_b128 v[166:169], v156 offset:33856
	s_waitcnt lgkmcnt(0)
	v_mfma_f32_16x16x32_bf16 v[110:113], v[166:169], v[134:137], v[110:113]
	ds_read_b128 v[166:169], v156 offset:33920
	s_waitcnt lgkmcnt(0)
	v_mfma_f32_16x16x32_bf16 v[110:113], v[166:169], v[138:141], v[110:113]
	ds_read_b128 v[166:169], v156 offset:33984
	s_waitcnt lgkmcnt(0)
	v_mfma_f32_16x16x32_bf16 v[110:113], v[166:169], v[142:145], v[110:113]
	ds_read_b128 v[166:169], v156 offset:42432
	ds_read_b128 v[170:173], v156 offset:42368
	ds_read_b128 v[174:177], v156 offset:42304
	ds_read_b128 v[178:181], v156 offset:42240
	s_waitcnt lgkmcnt(0)
	v_mfma_f32_16x16x32_bf16 v[106:109], v[178:181], v[130:133], v[106:109]
	v_mfma_f32_16x16x32_bf16 v[106:109], v[174:177], v[134:137], v[106:109]
	v_mfma_f32_16x16x32_bf16 v[106:109], v[170:173], v[138:141], v[106:109]
	v_mfma_f32_16x16x32_bf16 v[106:109], v[166:169], v[142:145], v[106:109]
	ds_read_b128 v[166:169], v156 offset:50688
	s_waitcnt lgkmcnt(0)
	v_mfma_f32_16x16x32_bf16 v[102:105], v[166:169], v[130:133], v[102:105]
	ds_read_b128 v[166:169], v156 offset:50752
	s_waitcnt lgkmcnt(0)
	v_mfma_f32_16x16x32_bf16 v[102:105], v[166:169], v[134:137], v[102:105]
	ds_read_b128 v[166:169], v156 offset:50816
	s_waitcnt lgkmcnt(0)
	v_mfma_f32_16x16x32_bf16 v[102:105], v[166:169], v[138:141], v[102:105]
	ds_read_b128 v[166:169], v156 offset:50880
	s_waitcnt lgkmcnt(0)
	v_mfma_f32_16x16x32_bf16 v[102:105], v[166:169], v[142:145], v[102:105]
	ds_read_b128 v[166:169], v156 offset:59328
	ds_read_b128 v[170:173], v156 offset:59264
	ds_read_b128 v[174:177], v156 offset:59200
	ds_read_b128 v[178:181], v156 offset:59136
	s_waitcnt lgkmcnt(0)
	v_mfma_f32_16x16x32_bf16 v[98:101], v[178:181], v[130:133], v[98:101]
	v_mfma_f32_16x16x32_bf16 v[98:101], v[174:177], v[134:137], v[98:101]
	v_mfma_f32_16x16x32_bf16 v[98:101], v[170:173], v[138:141], v[98:101]
	v_mfma_f32_16x16x32_bf16 v[98:101], v[166:169], v[142:145], v[98:101]
	ds_read_b128 v[166:169], v164
	s_waitcnt lgkmcnt(0)
	v_mfma_f32_16x16x32_bf16 v[94:97], v[166:169], v[130:133], v[94:97]
	ds_read_b128 v[166:169], v164 offset:64
	s_waitcnt lgkmcnt(0)
	v_mfma_f32_16x16x32_bf16 v[94:97], v[166:169], v[134:137], v[94:97]
	ds_read_b128 v[166:169], v164 offset:128
	s_waitcnt lgkmcnt(0)
	v_mfma_f32_16x16x32_bf16 v[94:97], v[166:169], v[138:141], v[94:97]
	ds_read_b128 v[164:167], v164 offset:192
	s_waitcnt lgkmcnt(0)
	v_mfma_f32_16x16x32_bf16 v[94:97], v[164:167], v[142:145], v[94:97]
	ds_read_b128 v[164:167], v163
	s_waitcnt lgkmcnt(0)
	v_mfma_f32_16x16x32_bf16 v[90:93], v[164:167], v[130:133], v[90:93]
	ds_read_b128 v[164:167], v163 offset:64
	s_waitcnt lgkmcnt(0)
	v_mfma_f32_16x16x32_bf16 v[90:93], v[164:167], v[134:137], v[90:93]
	ds_read_b128 v[164:167], v163 offset:128
	s_waitcnt lgkmcnt(0)
	v_mfma_f32_16x16x32_bf16 v[90:93], v[164:167], v[138:141], v[90:93]
	ds_read_b128 v[164:167], v163 offset:192
	s_waitcnt lgkmcnt(0)
	v_mfma_f32_16x16x32_bf16 v[90:93], v[164:167], v[142:145], v[90:93]
	ds_read_b128 v[164:167], v162
	s_waitcnt lgkmcnt(0)
	v_mfma_f32_16x16x32_bf16 v[86:89], v[164:167], v[130:133], v[86:89]
	ds_read_b128 v[164:167], v162 offset:64
	s_waitcnt lgkmcnt(0)
	v_mfma_f32_16x16x32_bf16 v[86:89], v[164:167], v[134:137], v[86:89]
	ds_read_b128 v[164:167], v162 offset:128
	s_waitcnt lgkmcnt(0)
	v_mfma_f32_16x16x32_bf16 v[86:89], v[164:167], v[138:141], v[86:89]
	ds_read_b128 v[162:165], v162 offset:192
	s_waitcnt lgkmcnt(0)
; #define LAS __attribute__((address_space(3)))
; __device__ __forceinline__ unsigned pk2(float lo, float hi) { const f32x2 v = {lo, hi}; return __builtin_bit_cast(unsigned, __builtin_convertvector(v, bf16x2_t)); }
; __device__ __forceinline__ f32x4 mfma16(bf16x8 a, bf16x8 b, f32x4 c) { return __builtin_amdgcn_mfma_f32_16x16x32_bf16(a, b, c, 0, 0, 0); }
; __device__ __forceinline__ void ret_out(const bf16* proj, const bf16* ST, bf16* mixed, const float* dexp, LAS unsigned char* lds, int vb, int nb, int tid_in0, int wave) {
;     ...
;                     bf16x8 qs[4];
; #pragma unroll
;                     for (int k4 = 0; k4 < 4; ++k4) { const int ks = 4 * kh + k4; const v4u q = *(const v4u*)(proj + (size_t)qrow * NIN + C_RQ + h * 256 + ks * 32 + g * 8); v4u r;
;                         r.x = pk2(bflo(q.x) * xi, bfhi(q.x) * xi); r.y = pk2(bflo(q.y) * xi, bfhi(q.y) * xi); r.z = pk2(bflo(q.z) * xi, bfhi(q.z) * xi); r.w = pk2(bflo(q.w) * xi, bfhi(q.w) * xi);
;                         qs[k4] = __builtin_bit_cast(bf16x8, r); }
; #pragma unroll
;                     for (int v = 0; v < 16; ++v) {
;                         const LAS unsigned char* sp = Sx + (v * 16 + qi) * 528 + g * 16 + kh * 256;
; #pragma unroll
;                         for (int k4 = 0; k4 < 4; ++k4) o[v] = mfma16(*(const LAS bf16x8*)(sp + k4 * 64), qs[k4], o[v]);
;                         if ((v & 1) == 1) asm volatile("" ::: "memory");
;                     }
	v_mfma_f32_16x16x32_bf16 v[86:89], v[162:165], v[142:145], v[86:89]
	ds_read_b128 v[162:165], v161
	s_waitcnt lgkmcnt(0)
	v_mfma_f32_16x16x32_bf16 v[82:85], v[162:165], v[130:133], v[82:85]
	ds_read_b128 v[162:165], v161 offset:64
	s_waitcnt lgkmcnt(0)
	v_mfma_f32_16x16x32_bf16 v[82:85], v[162:165], v[134:137], v[82:85]
	ds_read_b128 v[162:165], v161 offset:128
	s_waitcnt lgkmcnt(0)
	v_mfma_f32_16x16x32_bf16 v[82:85], v[162:165], v[138:141], v[82:85]
	ds_read_b128 v[162:165], v161 offset:192
	s_waitcnt lgkmcnt(0)
	v_mfma_f32_16x16x32_bf16 v[82:85], v[162:165], v[142:145], v[82:85]
	ds_read_b128 v[162:165], v160
	s_waitcnt lgkmcnt(0)
	v_mfma_f32_16x16x32_bf16 v[78:81], v[162:165], v[130:133], v[78:81]
	ds_read_b128 v[162:165], v160 offset:64
	s_waitcnt lgkmcnt(0)
	v_mfma_f32_16x16x32_bf16 v[78:81], v[162:165], v[134:137], v[78:81]
	ds_read_b128 v[162:165], v160 offset:128
	s_waitcnt lgkmcnt(0)
	v_mfma_f32_16x16x32_bf16 v[78:81], v[162:165], v[138:141], v[78:81]
	ds_read_b128 v[160:163], v160 offset:192
	s_waitcnt lgkmcnt(0)
	v_mfma_f32_16x16x32_bf16 v[78:81], v[160:163], v[142:145], v[78:81]
	ds_read_b128 v[160:163], v159
	s_waitcnt lgkmcnt(0)
	v_mfma_f32_16x16x32_bf16 v[74:77], v[160:163], v[130:133], v[74:77]
	ds_read_b128 v[160:163], v159 offset:64
	s_waitcnt lgkmcnt(0)
	v_mfma_f32_16x16x32_bf16 v[74:77], v[160:163], v[134:137], v[74:77]
	ds_read_b128 v[160:163], v159 offset:128
	s_waitcnt lgkmcnt(0)
	v_mfma_f32_16x16x32_bf16 v[74:77], v[160:163], v[138:141], v[74:77]
	ds_read_b128 v[160:163], v159 offset:192
	s_waitcnt lgkmcnt(0)
	v_mfma_f32_16x16x32_bf16 v[74:77], v[160:163], v[142:145], v[74:77]
	ds_read_b128 v[160:163], v158
	s_waitcnt lgkmcnt(0)
	v_mfma_f32_16x16x32_bf16 v[70:73], v[160:163], v[130:133], v[70:73]
	ds_read_b128 v[160:163], v158 offset:64
	s_waitcnt lgkmcnt(0)
	v_mfma_f32_16x16x32_bf16 v[70:73], v[160:163], v[134:137], v[70:73]
	ds_read_b128 v[160:163], v158 offset:128
	s_waitcnt lgkmcnt(0)
	v_mfma_f32_16x16x32_bf16 v[70:73], v[160:163], v[138:141], v[70:73]
	ds_read_b128 v[158:161], v158 offset:192
	s_waitcnt lgkmcnt(0)
	v_mfma_f32_16x16x32_bf16 v[70:73], v[158:161], v[142:145], v[70:73]
	ds_read_b128 v[158:161], v157
	s_waitcnt lgkmcnt(0)
	v_mfma_f32_16x16x32_bf16 v[66:69], v[158:161], v[130:133], v[66:69]
	ds_read_b128 v[130:133], v157 offset:64
	s_waitcnt lgkmcnt(0)
	v_mfma_f32_16x16x32_bf16 v[66:69], v[130:133], v[134:137], v[66:69]
	ds_read_b128 v[130:133], v157 offset:128
	s_waitcnt lgkmcnt(0)
	v_mfma_f32_16x16x32_bf16 v[66:69], v[130:133], v[138:141], v[66:69]
	ds_read_b128 v[130:133], v157 offset:192
	s_waitcnt lgkmcnt(0)
	v_mfma_f32_16x16x32_bf16 v[66:69], v[130:133], v[142:145], v[66:69]
	global_load_dwordx4 v[130:133], v[202:203], off offset:256
	s_waitcnt vmcnt(0)
	v_lshlrev_b32_e32 v134, 16, v130
	v_and_b32_e32 v135, 0xffff0000, v130
	v_pk_mul_f32 v[134:135], v[146:147], v[134:135] op_sel_hi:[0,1]
	v_cvt_pk_bf16_f32 v130, v134, v135
	v_lshlrev_b32_e32 v134, 16, v131
	v_and_b32_e32 v135, 0xffff0000, v131
	v_pk_mul_f32 v[134:135], v[146:147], v[134:135] op_sel_hi:[0,1]
	v_cvt_pk_bf16_f32 v131, v134, v135
	v_lshlrev_b32_e32 v134, 16, v132
	v_and_b32_e32 v135, 0xffff0000, v132
	v_pk_mul_f32 v[134:135], v[146:147], v[134:135] op_sel_hi:[0,1]
	v_cvt_pk_bf16_f32 v132, v134, v135
	v_lshlrev_b32_e32 v134, 16, v133
	v_and_b32_e32 v135, 0xffff0000, v133
	v_pk_mul_f32 v[134:135], v[146:147], v[134:135] op_sel_hi:[0,1]
	v_cvt_pk_bf16_f32 v133, v134, v135
	global_load_dwordx4 v[134:137], v[202:203], off offset:320
	s_waitcnt vmcnt(0)
	v_lshlrev_b32_e32 v138, 16, v134
	v_and_b32_e32 v139, 0xffff0000, v134
	v_pk_mul_f32 v[138:139], v[146:147], v[138:139] op_sel_hi:[0,1]
	v_cvt_pk_bf16_f32 v134, v138, v139
	v_lshlrev_b32_e32 v138, 16, v135
	v_and_b32_e32 v139, 0xffff0000, v135
	v_pk_mul_f32 v[138:139], v[146:147], v[138:139] op_sel_hi:[0,1]
	v_cvt_pk_bf16_f32 v135, v138, v139
	v_lshlrev_b32_e32 v138, 16, v136
	v_and_b32_e32 v139, 0xffff0000, v136
	v_pk_mul_f32 v[138:139], v[146:147], v[138:139] op_sel_hi:[0,1]
	v_cvt_pk_bf16_f32 v136, v138, v139
	v_lshlrev_b32_e32 v138, 16, v137
	v_and_b32_e32 v139, 0xffff0000, v137
	v_pk_mul_f32 v[138:139], v[146:147], v[138:139] op_sel_hi:[0,1]
	v_cvt_pk_bf16_f32 v137, v138, v139
	global_load_dwordx4 v[138:141], v[202:203], off offset:384
	s_waitcnt vmcnt(0)
	v_lshlrev_b32_e32 v142, 16, v138
	v_and_b32_e32 v143, 0xffff0000, v138
	v_pk_mul_f32 v[142:143], v[146:147], v[142:143] op_sel_hi:[0,1]
	v_cvt_pk_bf16_f32 v138, v142, v143
	v_lshlrev_b32_e32 v142, 16, v139
	v_and_b32_e32 v143, 0xffff0000, v139
	v_pk_mul_f32 v[142:143], v[146:147], v[142:143] op_sel_hi:[0,1]
	v_cvt_pk_bf16_f32 v139, v142, v143
	v_lshlrev_b32_e32 v142, 16, v140
	v_and_b32_e32 v143, 0xffff0000, v140
	v_pk_mul_f32 v[142:143], v[146:147], v[142:143] op_sel_hi:[0,1]
	v_cvt_pk_bf16_f32 v140, v142, v143
	v_lshlrev_b32_e32 v142, 16, v141
	v_and_b32_e32 v143, 0xffff0000, v141
	v_pk_mul_f32 v[142:143], v[146:147], v[142:143] op_sel_hi:[0,1]
	v_cvt_pk_bf16_f32 v141, v142, v143
	global_load_dwordx4 v[142:145], v[202:203], off offset:448
	s_waitcnt vmcnt(0)
	v_lshlrev_b32_e32 v158, 16, v142
	v_and_b32_e32 v159, 0xffff0000, v142
	v_pk_mul_f32 v[158:159], v[146:147], v[158:159] op_sel_hi:[0,1]
	v_cvt_pk_bf16_f32 v142, v158, v159
	v_lshlrev_b32_e32 v158, 16, v143
	v_and_b32_e32 v159, 0xffff0000, v143
	v_pk_mul_f32 v[158:159], v[146:147], v[158:159] op_sel_hi:[0,1]
	v_cvt_pk_bf16_f32 v143, v158, v159
	v_lshlrev_b32_e32 v158, 16, v144
	v_and_b32_e32 v159, 0xffff0000, v144
	v_pk_mul_f32 v[158:159], v[146:147], v[158:159] op_sel_hi:[0,1]
	v_cvt_pk_bf16_f32 v144, v158, v159
	v_lshlrev_b32_e32 v158, 16, v145
	v_and_b32_e32 v159, 0xffff0000, v145
	v_pk_mul_f32 v[158:159], v[146:147], v[158:159] op_sel_hi:[0,1]
	v_cvt_pk_bf16_f32 v145, v158, v159
	ds_read_b128 v[158:161], v156 offset:256
	s_waitcnt lgkmcnt(0)
; #define LAS __attribute__((address_space(3)))
; __device__ __forceinline__ f32x4 mfma16(bf16x8 a, bf16x8 b, f32x4 c) { return __builtin_amdgcn_mfma_f32_16x16x32_bf16(a, b, c, 0, 0, 0); }
; __device__ __forceinline__ void ret_out(const bf16* proj, const bf16* ST, bf16* mixed, const float* dexp, LAS unsigned char* lds, int vb, int nb, int tid_in0, int wave) {
;     ...
; #pragma unroll
;                     for (int v = 0; v < 16; ++v) {
;                         const LAS unsigned char* sp = Sx + (v * 16 + qi) * 528 + g * 16 + kh * 256;
; #pragma unroll
;                         for (int k4 = 0; k4 < 4; ++k4) o[v] = mfma16(*(const LAS bf16x8*)(sp + k4 * 64), qs[k4], o[v]);
;                         if ((v & 1) == 1) asm volatile("" ::: "memory");
;                     }
	v_mfma_f32_16x16x32_bf16 v[122:125], v[158:161], v[130:133], v[122:125]
	ds_read_b128 v[158:161], v156 offset:320
	v_add_u32_e32 v146, v148, v155
	s_waitcnt lgkmcnt(0)
	v_mfma_f32_16x16x32_bf16 v[122:125], v[158:161], v[134:137], v[122:125]
	ds_read_b128 v[158:161], v156 offset:384
	s_waitcnt lgkmcnt(0)
	v_mfma_f32_16x16x32_bf16 v[122:125], v[158:161], v[138:141], v[122:125]
	ds_read_b128 v[158:161], v156 offset:448
	s_waitcnt lgkmcnt(0)
	v_mfma_f32_16x16x32_bf16 v[122:125], v[158:161], v[142:145], v[122:125]
	ds_read_b128 v[158:161], v156 offset:8896
	ds_read_b128 v[162:165], v156 offset:8832
	ds_read_b128 v[166:169], v156 offset:8768
	ds_read_b128 v[170:173], v156 offset:8704
	s_waitcnt lgkmcnt(0)
	v_mfma_f32_16x16x32_bf16 v[126:129], v[170:173], v[130:133], v[126:129]
	v_mfma_f32_16x16x32_bf16 v[126:129], v[166:169], v[134:137], v[126:129]
	v_mfma_f32_16x16x32_bf16 v[126:129], v[162:165], v[138:141], v[126:129]
	v_mfma_f32_16x16x32_bf16 v[126:129], v[158:161], v[142:145], v[126:129]
	ds_read_b128 v[158:161], v156 offset:17152
	s_waitcnt lgkmcnt(0)
	v_mfma_f32_16x16x32_bf16 v[118:121], v[158:161], v[130:133], v[118:121]
	ds_read_b128 v[158:161], v156 offset:17216
	s_waitcnt lgkmcnt(0)
	v_mfma_f32_16x16x32_bf16 v[118:121], v[158:161], v[134:137], v[118:121]
	ds_read_b128 v[158:161], v156 offset:17280
	s_waitcnt lgkmcnt(0)
	v_mfma_f32_16x16x32_bf16 v[118:121], v[158:161], v[138:141], v[118:121]
	ds_read_b128 v[158:161], v156 offset:17344
	s_waitcnt lgkmcnt(0)
	v_mfma_f32_16x16x32_bf16 v[118:121], v[158:161], v[142:145], v[118:121]
	ds_read_b128 v[158:161], v156 offset:25792
	ds_read_b128 v[162:165], v156 offset:25728
	ds_read_b128 v[166:169], v156 offset:25664
	ds_read_b128 v[170:173], v156 offset:25600
	s_waitcnt lgkmcnt(0)
	v_mfma_f32_16x16x32_bf16 v[114:117], v[170:173], v[130:133], v[114:117]
	v_mfma_f32_16x16x32_bf16 v[114:117], v[166:169], v[134:137], v[114:117]
	v_mfma_f32_16x16x32_bf16 v[114:117], v[162:165], v[138:141], v[114:117]
	v_mfma_f32_16x16x32_bf16 v[114:117], v[158:161], v[142:145], v[114:117]
	ds_read_b128 v[158:161], v156 offset:34048
	s_waitcnt lgkmcnt(0)
	v_mfma_f32_16x16x32_bf16 v[110:113], v[158:161], v[130:133], v[110:113]
	ds_read_b128 v[158:161], v156 offset:34112
	s_waitcnt lgkmcnt(0)
	v_mfma_f32_16x16x32_bf16 v[110:113], v[158:161], v[134:137], v[110:113]
	ds_read_b128 v[158:161], v156 offset:34176
	s_waitcnt lgkmcnt(0)
	v_mfma_f32_16x16x32_bf16 v[110:113], v[158:161], v[138:141], v[110:113]
	ds_read_b128 v[158:161], v156 offset:34240
	s_waitcnt lgkmcnt(0)
	v_mfma_f32_16x16x32_bf16 v[110:113], v[158:161], v[142:145], v[110:113]
	ds_read_b128 v[158:161], v156 offset:42688
	ds_read_b128 v[162:165], v156 offset:42624
	ds_read_b128 v[166:169], v156 offset:42560
	ds_read_b128 v[170:173], v156 offset:42496
	s_waitcnt lgkmcnt(0)
	v_mfma_f32_16x16x32_bf16 v[106:109], v[170:173], v[130:133], v[106:109]
	v_mfma_f32_16x16x32_bf16 v[106:109], v[166:169], v[134:137], v[106:109]
	v_mfma_f32_16x16x32_bf16 v[106:109], v[162:165], v[138:141], v[106:109]
	v_mfma_f32_16x16x32_bf16 v[106:109], v[158:161], v[142:145], v[106:109]
	ds_read_b128 v[158:161], v156 offset:50944
	s_waitcnt lgkmcnt(0)
	v_mfma_f32_16x16x32_bf16 v[102:105], v[158:161], v[130:133], v[102:105]
	ds_read_b128 v[158:161], v156 offset:51008
	s_waitcnt lgkmcnt(0)
	v_mfma_f32_16x16x32_bf16 v[102:105], v[158:161], v[134:137], v[102:105]
	ds_read_b128 v[158:161], v156 offset:51072
	s_waitcnt lgkmcnt(0)
	v_mfma_f32_16x16x32_bf16 v[102:105], v[158:161], v[138:141], v[102:105]
	ds_read_b128 v[158:161], v156 offset:51136
	s_waitcnt lgkmcnt(0)
	v_mfma_f32_16x16x32_bf16 v[102:105], v[158:161], v[142:145], v[102:105]
	ds_read_b128 v[158:161], v156 offset:59584
	ds_read_b128 v[162:165], v156 offset:59520
	ds_read_b128 v[166:169], v156 offset:59456
	ds_read_b128 v[170:173], v156 offset:59392
	s_waitcnt lgkmcnt(0)
	v_mfma_f32_16x16x32_bf16 v[98:101], v[170:173], v[130:133], v[98:101]
	v_mfma_f32_16x16x32_bf16 v[98:101], v[166:169], v[134:137], v[98:101]
	v_mfma_f32_16x16x32_bf16 v[98:101], v[162:165], v[138:141], v[98:101]
	v_mfma_f32_16x16x32_bf16 v[98:101], v[158:161], v[142:145], v[98:101]
	ds_read_b128 v[156:159], v146
	s_waitcnt lgkmcnt(0)
; #define LAS __attribute__((address_space(3)))
; __device__ __forceinline__ f32x4 mfma16(bf16x8 a, bf16x8 b, f32x4 c) { return __builtin_amdgcn_mfma_f32_16x16x32_bf16(a, b, c, 0, 0, 0); }
; __device__ __forceinline__ void ret_out(const bf16* proj, const bf16* ST, bf16* mixed, const float* dexp, LAS unsigned char* lds, int vb, int nb, int tid_in0, int wave) {
;     ...
; #pragma unroll
;                     for (int v = 0; v < 16; ++v) {
;                         const LAS unsigned char* sp = Sx + (v * 16 + qi) * 528 + g * 16 + kh * 256;
; #pragma unroll
;                         for (int k4 = 0; k4 < 4; ++k4) o[v] = mfma16(*(const LAS bf16x8*)(sp + k4 * 64), qs[k4], o[v]);
;                         if ((v & 1) == 1) asm volatile("" ::: "memory");
;                     }
	v_mfma_f32_16x16x32_bf16 v[94:97], v[156:159], v[130:133], v[94:97]
	ds_read_b128 v[156:159], v146 offset:64
	s_waitcnt lgkmcnt(0)
	v_mfma_f32_16x16x32_bf16 v[94:97], v[156:159], v[134:137], v[94:97]
	ds_read_b128 v[156:159], v146 offset:128
	s_waitcnt lgkmcnt(0)
	v_mfma_f32_16x16x32_bf16 v[94:97], v[156:159], v[138:141], v[94:97]
	ds_read_b128 v[156:159], v146 offset:192
	v_add_u32_e32 v146, v148, v154
	s_waitcnt lgkmcnt(0)
	v_mfma_f32_16x16x32_bf16 v[94:97], v[156:159], v[142:145], v[94:97]
	ds_read_b128 v[154:157], v146 offset:192
	ds_read_b128 v[158:161], v146 offset:128
	ds_read_b128 v[162:165], v146 offset:64
	ds_read_b128 v[166:169], v146
	v_add_u32_e32 v146, v148, v153
	s_waitcnt lgkmcnt(0)
	v_mfma_f32_16x16x32_bf16 v[90:93], v[166:169], v[130:133], v[90:93]
	v_mfma_f32_16x16x32_bf16 v[90:93], v[162:165], v[134:137], v[90:93]
	v_mfma_f32_16x16x32_bf16 v[90:93], v[158:161], v[138:141], v[90:93]
	v_mfma_f32_16x16x32_bf16 v[90:93], v[154:157], v[142:145], v[90:93]
	ds_read_b128 v[154:157], v146
	s_waitcnt lgkmcnt(0)
	v_mfma_f32_16x16x32_bf16 v[86:89], v[154:157], v[130:133], v[86:89]
	ds_read_b128 v[154:157], v146 offset:64
	s_waitcnt lgkmcnt(0)
	v_mfma_f32_16x16x32_bf16 v[86:89], v[154:157], v[134:137], v[86:89]
	ds_read_b128 v[154:157], v146 offset:128
	s_waitcnt lgkmcnt(0)
	v_mfma_f32_16x16x32_bf16 v[86:89], v[154:157], v[138:141], v[86:89]
	ds_read_b128 v[154:157], v146 offset:192
	v_add_u32_e32 v146, v148, v152
	s_waitcnt lgkmcnt(0)
	v_mfma_f32_16x16x32_bf16 v[86:89], v[154:157], v[142:145], v[86:89]
	ds_read_b128 v[152:155], v146 offset:192
	ds_read_b128 v[156:159], v146 offset:128
	ds_read_b128 v[160:163], v146 offset:64
	ds_read_b128 v[164:167], v146
	v_add_u32_e32 v146, v148, v151
	s_waitcnt lgkmcnt(0)
	v_mfma_f32_16x16x32_bf16 v[82:85], v[164:167], v[130:133], v[82:85]
	v_mfma_f32_16x16x32_bf16 v[82:85], v[160:163], v[134:137], v[82:85]
	v_mfma_f32_16x16x32_bf16 v[82:85], v[156:159], v[138:141], v[82:85]
	v_mfma_f32_16x16x32_bf16 v[82:85], v[152:155], v[142:145], v[82:85]
	ds_read_b128 v[152:155], v146
	s_waitcnt lgkmcnt(0)
	v_mfma_f32_16x16x32_bf16 v[78:81], v[152:155], v[130:133], v[78:81]
	ds_read_b128 v[152:155], v146 offset:64
	s_waitcnt lgkmcnt(0)
	v_mfma_f32_16x16x32_bf16 v[78:81], v[152:155], v[134:137], v[78:81]
	ds_read_b128 v[152:155], v146 offset:128
	s_waitcnt lgkmcnt(0)
	v_mfma_f32_16x16x32_bf16 v[78:81], v[152:155], v[138:141], v[78:81]
	ds_read_b128 v[152:155], v146 offset:192
	v_add_u32_e32 v146, v148, v150
	s_waitcnt lgkmcnt(0)
	v_mfma_f32_16x16x32_bf16 v[78:81], v[152:155], v[142:145], v[78:81]
	ds_read_b128 v[150:153], v146 offset:192
	ds_read_b128 v[154:157], v146 offset:128
	ds_read_b128 v[158:161], v146 offset:64
	ds_read_b128 v[162:165], v146
	v_add_u32_e32 v146, v148, v149
	s_waitcnt lgkmcnt(0)
	v_mfma_f32_16x16x32_bf16 v[74:77], v[162:165], v[130:133], v[74:77]
	v_mfma_f32_16x16x32_bf16 v[74:77], v[158:161], v[134:137], v[74:77]
	v_add_u32_e32 v158, v148, v147
	v_mfma_f32_16x16x32_bf16 v[74:77], v[154:157], v[138:141], v[74:77]
	v_mfma_f32_16x16x32_bf16 v[74:77], v[150:153], v[142:145], v[74:77]
	ds_read_b128 v[150:153], v146
	s_waitcnt lgkmcnt(0)
	v_mfma_f32_16x16x32_bf16 v[70:73], v[150:153], v[130:133], v[70:73]
	ds_read_b128 v[150:153], v146 offset:64
	s_waitcnt lgkmcnt(0)
	v_mfma_f32_16x16x32_bf16 v[70:73], v[150:153], v[134:137], v[70:73]
	ds_read_b128 v[150:153], v146 offset:128
	s_waitcnt lgkmcnt(0)
	v_mfma_f32_16x16x32_bf16 v[70:73], v[150:153], v[138:141], v[70:73]
	ds_read_b128 v[150:153], v146 offset:192
	s_waitcnt lgkmcnt(0)
	v_mfma_f32_16x16x32_bf16 v[70:73], v[150:153], v[142:145], v[70:73]
	ds_read_b128 v[146:149], v158 offset:192
	ds_read_b128 v[150:153], v158 offset:128
	ds_read_b128 v[154:157], v158 offset:64
	ds_read_b128 v[158:161], v158
	s_waitcnt lgkmcnt(0)
	v_mfma_f32_16x16x32_bf16 v[66:69], v[158:161], v[130:133], v[66:69]
	v_mfma_f32_16x16x32_bf16 v[66:69], v[154:157], v[134:137], v[66:69]
	v_mfma_f32_16x16x32_bf16 v[66:69], v[150:153], v[138:141], v[66:69]
	v_mfma_f32_16x16x32_bf16 v[66:69], v[146:149], v[142:145], v[66:69]
	s_branch .LBB0_833
